# code placement: every 16-MFMA group of the six GEMM K-loops starts 8-byte aligned (8 s_nop words in load segments), on the combined version
# speedup vs baseline: 1.0045x; 1.0045x over previous
; #define PG8_STAGE(bufoff, gbase, voff) do { _Pragma("unroll") for (int _i = 0; _i < 2; ++_i) \
;         __builtin_amdgcn_global_load_lds((const unsigned*)((const char*)(gbase) + (voff)[_i]), (PG8_LAS unsigned*)(lds + (bufoff) + ldsw + _i * 8192), 16, 0, 0); } while (0)
; #define PG8_LDA(dst, b, h) do { _Pragma("unroll") for (int m = 0; m < 4; ++m) _Pragma("unroll") for (int k = 0; k < 2; ++k) dst[m][k] = *(const PG8_LAS bf16x8*)(lds + PG8_SA(b, h) + aoff + m * 2048 + k * 1024); } while (0)
; #define PG8_LDB(dst, b, h) do { _Pragma("unroll") for (int n = 0; n < 2; ++n) _Pragma("unroll") for (int k = 0; k < 2; ++k) dst[n][k] = *(const PG8_LAS bf16x8*)(lds + PG8_SB(b, h) + boff + n * 2048 + k * 1024); } while (0)
; #define PG8_MMA(ai, bj, At, Bt) do { __builtin_amdgcn_s_setprio(1); _Pragma("unroll") for (int m = 0; m < 4; ++m) _Pragma("unroll") for (int n = 0; n < 2; ++n) _Pragma("unroll") for (int k = 0; k < 2; ++k) \
;         acc[ai][bj][m][n] = __builtin_amdgcn_mfma_f32_16x16x32_bf16(Bt[n][k], At[m][k], acc[ai][bj][m][n], 0, 0, 0); __builtin_amdgcn_s_setprio(0); } while (0)
; #define PG8_WAIT_V(n) asm volatile("s_waitcnt vmcnt(" #n ")" ::: "memory")
; #define PG8_BAR __builtin_amdgcn_s_barrier()
; template <class Epi, class Sched, bool ALIGN_EPI = false, bool SP2 = false>
; __device__ __forceinline__ void gemm_phase(PG8_LAS unsigned char* lds, const Gemm g, const Sched& S, const Epi& E, int wave_s) {
;     ...
;         for (int t = 0; t < nt; t += 2) {
;             const bool last = (t == nt - 2);
;             const char* a1 = cA + (size_t)(t + 1) * kstep;
;             const char* a2 = last ? nA : cA + (size_t)(t + 2) * kstep; const char* b2 = last ? nB : cB + (size_t)(t + 2) * kstep;
;             const char* a3 = a2 + kstep; const char* b3 = b2 + kstep;
;             if (last && has_next) S.a_ready(nxt);
;             if constexpr (SP2) {
;             PG8_LDB(B0, 0, 0); PG8_LDB(B1, 0, 1); PG8_SCHED; PG8_LDA(At, 0, 0); PG8_STAGE(PG8_SA(1, 1), a1 + hstepA, voffA);
;             PG8_WAIT_V(8); PG8_WAIT_L(0); PG8_BAR; PG8_MMA(0, 0, At, B0); PG8_MMA(0, 1, At, B1); PG8_BAR; PG8_SCHED;
;             PG8_LDA(At, 0, 1); PG8_STAGE(PG8_SB(0, 0), b2, voffB); PG8_STAGE(PG8_SB(0, 1), b2 + hstepB, voffB); PG8_STAGE(PG8_SA(0, 0), a2, voffA);
;             PG8_WAIT_V(8); PG8_WAIT_L(0); PG8_BAR; PG8_MMA(1, 0, At, B0); PG8_MMA(1, 1, At, B1); PG8_BAR; PG8_SCHED;
.LBB0_192:
	s_add_u32 s26, s18, 0xfff80080
	s_addc_u32 s27, s19, -1
	s_add_i32 s56, 0, 0x10000
	s_cmp_eq_u32 s55, 28
	s_cselect_b32 s37, s23, s27
	s_cselect_b32 s36, s39, s26
	s_cselect_b32 s27, s21, s54
	s_cselect_b32 s26, s52, s53
	s_add_i32 s58, 0, 0x14000
	ds_read_b128 v[142:145], v255
	ds_read_b128 v[152:155], v255 offset:1024
	ds_read_b128 v[156:159], v255 offset:2048
	ds_read_b128 v[160:163], v255 offset:3072
	ds_read_b128 v[164:167], v255 offset:16384
	ds_read_b128 v[182:185], v255 offset:17408
	ds_read_b128 v[186:189], v255 offset:18432
	ds_read_b128 v[190:193], v255 offset:19456
	s_add_i32 m0, s45, 0xc000
	ds_read_b128 v[194:197], v151
	ds_read_b128 v[198:201], v151 offset:1024
	ds_read_b128 v[212:215], v151 offset:2048
	ds_read_b128 v[216:219], v151 offset:3072
	ds_read_b128 v[220:223], v151 offset:4096
	ds_read_b128 v[224:227], v151 offset:5120
	ds_read_b128 v[228:231], v151 offset:6144
	ds_read_b128 v[232:235], v151 offset:7168
	global_load_lds_dwordx4 v140, s[18:19]
	s_add_i32 m0, s45, 0xe000
	s_nop 0
	global_load_lds_dwordx4 v138, s[18:19]
	s_waitcnt vmcnt(8)
	s_waitcnt lgkmcnt(0)
	s_barrier
	s_setprio 1
	s_waitcnt lgkmcnt(0)
	v_mfma_f32_16x16x32_bf16 v[72:75], v[142:145], v[194:197], v[72:75]
	v_mfma_f32_16x16x32_bf16 v[68:71], v[156:159], v[194:197], v[68:71]
	v_mfma_f32_16x16x32_bf16 v[64:67], v[142:145], v[212:215], v[64:67]
	v_mfma_f32_16x16x32_bf16 v[60:63], v[156:159], v[212:215], v[60:63]
	v_mfma_f32_16x16x32_bf16 v[56:59], v[142:145], v[220:223], v[56:59]
	v_mfma_f32_16x16x32_bf16 v[52:55], v[156:159], v[220:223], v[52:55]
	v_mfma_f32_16x16x32_bf16 v[48:51], v[142:145], v[228:231], v[48:51]
	v_mfma_f32_16x16x32_bf16 v[44:47], v[156:159], v[228:231], v[44:47]
	v_mfma_f32_16x16x32_bf16 v[72:75], v[152:155], v[198:201], v[72:75]
	v_mfma_f32_16x16x32_bf16 v[68:71], v[160:163], v[198:201], v[68:71]
	v_mfma_f32_16x16x32_bf16 v[64:67], v[152:155], v[216:219], v[64:67]
	v_mfma_f32_16x16x32_bf16 v[60:63], v[160:163], v[216:219], v[60:63]
	v_mfma_f32_16x16x32_bf16 v[56:59], v[152:155], v[224:227], v[56:59]
	v_mfma_f32_16x16x32_bf16 v[52:55], v[160:163], v[224:227], v[52:55]
	v_mfma_f32_16x16x32_bf16 v[48:51], v[152:155], v[232:235], v[48:51]
	v_mfma_f32_16x16x32_bf16 v[44:47], v[160:163], v[232:235], v[44:47]
	s_setprio 0
	s_setprio 1
	v_mfma_f32_16x16x32_bf16 v[128:131], v[164:167], v[194:197], v[128:131]
	v_mfma_f32_16x16x32_bf16 v[124:127], v[186:189], v[194:197], v[124:127]
	v_mfma_f32_16x16x32_bf16 v[120:123], v[164:167], v[212:215], v[120:123]
	v_mfma_f32_16x16x32_bf16 v[116:119], v[186:189], v[212:215], v[116:119]
	v_mfma_f32_16x16x32_bf16 v[112:115], v[164:167], v[220:223], v[112:115]
	v_mfma_f32_16x16x32_bf16 v[108:111], v[186:189], v[220:223], v[108:111]
	v_mfma_f32_16x16x32_bf16 v[104:107], v[164:167], v[228:231], v[104:107]
	v_mfma_f32_16x16x32_bf16 v[100:103], v[186:189], v[228:231], v[100:103]
	v_mfma_f32_16x16x32_bf16 v[128:131], v[182:185], v[198:201], v[128:131]
	v_mfma_f32_16x16x32_bf16 v[124:127], v[190:193], v[198:201], v[124:127]
	v_mfma_f32_16x16x32_bf16 v[120:123], v[182:185], v[216:219], v[120:123]
	v_mfma_f32_16x16x32_bf16 v[116:119], v[190:193], v[216:219], v[116:119]
	v_mfma_f32_16x16x32_bf16 v[112:115], v[182:185], v[224:227], v[112:115]
	v_mfma_f32_16x16x32_bf16 v[108:111], v[190:193], v[224:227], v[108:111]
	v_mfma_f32_16x16x32_bf16 v[104:107], v[182:185], v[232:235], v[104:107]
	v_mfma_f32_16x16x32_bf16 v[100:103], v[190:193], v[232:235], v[100:103]
	s_setprio 0
	s_barrier
	s_add_i32 s56, s56, s44
	s_add_u32 s98, s26, s60
	s_addc_u32 s99, s27, s61
	s_mov_b32 m0, s56
	ds_read_b128 v[194:197], v151 offset:16384
	ds_read_b128 v[198:201], v151 offset:17408
	ds_read_b128 v[212:215], v151 offset:18432
	ds_read_b128 v[216:219], v151 offset:19456
	ds_read_b128 v[220:223], v151 offset:20480
	ds_read_b128 v[224:227], v151 offset:21504
	ds_read_b128 v[228:231], v151 offset:22528
	ds_read_b128 v[232:235], v151 offset:23552
	global_load_lds_dwordx4 v2, s[26:27]
	s_add_i32 m0, s56, 0x2000
	s_add_u32 s56, s26, 0x80000
	s_addc_u32 s57, s27, 0
	s_add_i32 s58, s58, s44
	global_load_lds_dwordx4 v0, s[26:27]
	s_mov_b32 m0, s58
	s_nop 0
	global_load_lds_dwordx4 v2, s[56:57]
	s_add_i32 m0, s58, 0x2000
	s_nop 0
	global_load_lds_dwordx4 v0, s[56:57]
	s_mov_b32 m0, s45
	s_nop 0
	global_load_lds_dwordx4 v134, s[36:37]
	s_mov_b32 m0, s46
	s_nop 0
	global_load_lds_dwordx4 v132, s[36:37]
	s_waitcnt vmcnt(8)
	s_waitcnt lgkmcnt(0)
	s_barrier
	s_setprio 1
	s_waitcnt lgkmcnt(0)
	v_mfma_f32_16x16x32_bf16 v[32:35], v[142:145], v[194:197], v[32:35]
	v_mfma_f32_16x16x32_bf16 v[28:31], v[156:159], v[194:197], v[28:31]
	v_mfma_f32_16x16x32_bf16 v[24:27], v[142:145], v[212:215], v[24:27]
	v_mfma_f32_16x16x32_bf16 v[20:23], v[156:159], v[212:215], v[20:23]
	v_mfma_f32_16x16x32_bf16 v[16:19], v[142:145], v[220:223], v[16:19]
	v_mfma_f32_16x16x32_bf16 v[12:15], v[156:159], v[220:223], v[12:15]
	v_mfma_f32_16x16x32_bf16 v[8:11], v[142:145], v[228:231], v[8:11]
	v_mfma_f32_16x16x32_bf16 v[4:7], v[156:159], v[228:231], v[4:7]
	v_mfma_f32_16x16x32_bf16 v[32:35], v[152:155], v[198:201], v[32:35]
	v_mfma_f32_16x16x32_bf16 v[28:31], v[160:163], v[198:201], v[28:31]
	v_mfma_f32_16x16x32_bf16 v[24:27], v[152:155], v[216:219], v[24:27]
	v_mfma_f32_16x16x32_bf16 v[20:23], v[160:163], v[216:219], v[20:23]
	v_mfma_f32_16x16x32_bf16 v[16:19], v[152:155], v[224:227], v[16:19]
	v_mfma_f32_16x16x32_bf16 v[12:15], v[160:163], v[224:227], v[12:15]
	v_mfma_f32_16x16x32_bf16 v[8:11], v[152:155], v[232:235], v[8:11]
	v_mfma_f32_16x16x32_bf16 v[4:7], v[160:163], v[232:235], v[4:7]
	s_setprio 0
	s_setprio 1
	v_mfma_f32_16x16x32_bf16 v[96:99], v[164:167], v[194:197], v[96:99]
	v_mfma_f32_16x16x32_bf16 v[92:95], v[186:189], v[194:197], v[92:95]
	v_mfma_f32_16x16x32_bf16 v[88:91], v[164:167], v[212:215], v[88:91]
	v_mfma_f32_16x16x32_bf16 v[84:87], v[186:189], v[212:215], v[84:87]
	v_mfma_f32_16x16x32_bf16 v[80:83], v[164:167], v[220:223], v[80:83]
	v_mfma_f32_16x16x32_bf16 v[76:79], v[186:189], v[220:223], v[76:79]
	v_mfma_f32_16x16x32_bf16 v[40:43], v[164:167], v[228:231], v[40:43]
	v_mfma_f32_16x16x32_bf16 v[36:39], v[186:189], v[228:231], v[36:39]
	v_mfma_f32_16x16x32_bf16 v[96:99], v[182:185], v[198:201], v[96:99]
	v_mfma_f32_16x16x32_bf16 v[92:95], v[190:193], v[198:201], v[92:95]
	v_mfma_f32_16x16x32_bf16 v[88:91], v[182:185], v[216:219], v[88:91]
	v_mfma_f32_16x16x32_bf16 v[84:87], v[190:193], v[216:219], v[84:87]
	v_mfma_f32_16x16x32_bf16 v[80:83], v[182:185], v[224:227], v[80:83]
	v_mfma_f32_16x16x32_bf16 v[76:79], v[190:193], v[224:227], v[76:79]
	v_mfma_f32_16x16x32_bf16 v[40:43], v[182:185], v[232:235], v[40:43]
	v_mfma_f32_16x16x32_bf16 v[36:39], v[190:193], v[232:235], v[36:39]
	s_setprio 0
	s_barrier
; #define PG8_STAGE(bufoff, gbase, voff) do { _Pragma("unroll") for (int _i = 0; _i < 2; ++_i) \
;         __builtin_amdgcn_global_load_lds((const unsigned*)((const char*)(gbase) + (voff)[_i]), (PG8_LAS unsigned*)(lds + (bufoff) + ldsw + _i * 8192), 16, 0, 0); } while (0)
; #define PG8_LDA(dst, b, h) do { _Pragma("unroll") for (int m = 0; m < 4; ++m) _Pragma("unroll") for (int k = 0; k < 2; ++k) dst[m][k] = *(const PG8_LAS bf16x8*)(lds + PG8_SA(b, h) + aoff + m * 2048 + k * 1024); } while (0)
; #define PG8_LDB(dst, b, h) do { _Pragma("unroll") for (int n = 0; n < 2; ++n) _Pragma("unroll") for (int k = 0; k < 2; ++k) dst[n][k] = *(const PG8_LAS bf16x8*)(lds + PG8_SB(b, h) + boff + n * 2048 + k * 1024); } while (0)
; #define PG8_MMA(ai, bj, At, Bt) do { __builtin_amdgcn_s_setprio(1); _Pragma("unroll") for (int m = 0; m < 4; ++m) _Pragma("unroll") for (int n = 0; n < 2; ++n) _Pragma("unroll") for (int k = 0; k < 2; ++k) \
;         acc[ai][bj][m][n] = __builtin_amdgcn_mfma_f32_16x16x32_bf16(Bt[n][k], At[m][k], acc[ai][bj][m][n], 0, 0, 0); __builtin_amdgcn_s_setprio(0); } while (0)
; #define PG8_WAIT_V(n) asm volatile("s_waitcnt vmcnt(" #n ")" ::: "memory")
; #define PG8_WAIT_L(n) asm volatile("s_waitcnt lgkmcnt(" #n ")" ::: "memory")
; #define PG8_BAR __builtin_amdgcn_s_barrier()
; #define PG8_SCHED __builtin_amdgcn_sched_barrier(0)
;     __device__ __forceinline__ void operator()(const f32x4 (&acc)[2][2][4][2], const Unit& u, int wr, int wc, int fr, int fq) const {
;         const int row0 = u.pm * BM + wr * 64 + fr;
;         if (u.pn == 74) {
; template <class Epi, class Sched, bool ALIGN_EPI = false, bool SP2 = false>
; __device__ __forceinline__ void gemm_phase(PG8_LAS unsigned char* lds, const Gemm g, const Sched& S, const Epi& E, int wave_s) {
;     ...
;             PG8_LDB(B0, 1, 0); PG8_LDB(B1, 1, 1); PG8_SCHED; PG8_LDA(At, 1, 0); PG8_STAGE(PG8_SA(0, 1), a2 + hstepA, voffA);
;             PG8_WAIT_V(8); PG8_WAIT_L(0); PG8_BAR; PG8_MMA(0, 0, At, B0); PG8_MMA(0, 1, At, B1); PG8_BAR; PG8_SCHED;
;             PG8_LDA(At, 1, 1); PG8_STAGE(PG8_SB(1, 0), b3, voffB); PG8_STAGE(PG8_SB(1, 1), b3 + hstepB, voffB); PG8_STAGE(PG8_SA(1, 0), a3, voffA);
;             PG8_WAIT_V(8); PG8_WAIT_L(0); PG8_BAR; PG8_MMA(1, 0, At, B0); PG8_MMA(1, 1, At, B1); PG8_BAR; PG8_SCHED;
	s_nop 0
	s_add_i32 s56, 0, 0x18000
	s_add_i32 s57, 0, 0x1c000
	ds_read_b128 v[142:145], v255 offset:32768
	ds_read_b128 v[152:155], v255 offset:33792
	ds_read_b128 v[156:159], v255 offset:34816
	ds_read_b128 v[160:163], v255 offset:35840
	ds_read_b128 v[164:167], v255 offset:49152
	ds_read_b128 v[182:185], v255 offset:50176
	ds_read_b128 v[186:189], v255 offset:51200
	ds_read_b128 v[190:193], v255 offset:52224
	s_add_u32 s100, s36, s60
	s_addc_u32 s101, s37, s61
	s_add_u32 s36, s36, 0x80000
	s_addc_u32 s37, s37, 0
	s_mov_b32 m0, s47
	ds_read_b128 v[194:197], v151 offset:32768
	ds_read_b128 v[198:201], v151 offset:33792
	ds_read_b128 v[212:215], v151 offset:34816
	ds_read_b128 v[216:219], v151 offset:35840
	ds_read_b128 v[220:223], v151 offset:36864
	ds_read_b128 v[224:227], v151 offset:37888
	ds_read_b128 v[228:231], v151 offset:38912
	ds_read_b128 v[232:235], v151 offset:39936
	global_load_lds_dwordx4 v134, s[36:37]
	s_mov_b32 m0, s48
	s_nop 0
	global_load_lds_dwordx4 v132, s[36:37]
	s_waitcnt vmcnt(8)
	s_waitcnt lgkmcnt(0)
	s_barrier
	s_setprio 1
	s_waitcnt lgkmcnt(0)
	v_mfma_f32_16x16x32_bf16 v[72:75], v[142:145], v[194:197], v[72:75]
	v_mfma_f32_16x16x32_bf16 v[68:71], v[156:159], v[194:197], v[68:71]
	v_mfma_f32_16x16x32_bf16 v[64:67], v[142:145], v[212:215], v[64:67]
	v_mfma_f32_16x16x32_bf16 v[60:63], v[156:159], v[212:215], v[60:63]
	v_mfma_f32_16x16x32_bf16 v[56:59], v[142:145], v[220:223], v[56:59]
	v_mfma_f32_16x16x32_bf16 v[52:55], v[156:159], v[220:223], v[52:55]
	v_mfma_f32_16x16x32_bf16 v[48:51], v[142:145], v[228:231], v[48:51]
	v_mfma_f32_16x16x32_bf16 v[44:47], v[156:159], v[228:231], v[44:47]
	v_mfma_f32_16x16x32_bf16 v[72:75], v[152:155], v[198:201], v[72:75]
	v_mfma_f32_16x16x32_bf16 v[68:71], v[160:163], v[198:201], v[68:71]
	v_mfma_f32_16x16x32_bf16 v[64:67], v[152:155], v[216:219], v[64:67]
	v_mfma_f32_16x16x32_bf16 v[60:63], v[160:163], v[216:219], v[60:63]
	v_mfma_f32_16x16x32_bf16 v[56:59], v[152:155], v[224:227], v[56:59]
	v_mfma_f32_16x16x32_bf16 v[52:55], v[160:163], v[224:227], v[52:55]
	v_mfma_f32_16x16x32_bf16 v[48:51], v[152:155], v[232:235], v[48:51]
	v_mfma_f32_16x16x32_bf16 v[44:47], v[160:163], v[232:235], v[44:47]
	s_setprio 0
	s_setprio 1
	v_mfma_f32_16x16x32_bf16 v[128:131], v[164:167], v[194:197], v[128:131]
	v_mfma_f32_16x16x32_bf16 v[124:127], v[186:189], v[194:197], v[124:127]
	v_mfma_f32_16x16x32_bf16 v[120:123], v[164:167], v[212:215], v[120:123]
	v_mfma_f32_16x16x32_bf16 v[116:119], v[186:189], v[212:215], v[116:119]
	v_mfma_f32_16x16x32_bf16 v[112:115], v[164:167], v[220:223], v[112:115]
	v_mfma_f32_16x16x32_bf16 v[108:111], v[186:189], v[220:223], v[108:111]
	v_mfma_f32_16x16x32_bf16 v[104:107], v[164:167], v[228:231], v[104:107]
	v_mfma_f32_16x16x32_bf16 v[100:103], v[186:189], v[228:231], v[100:103]
	v_mfma_f32_16x16x32_bf16 v[128:131], v[182:185], v[198:201], v[128:131]
	v_mfma_f32_16x16x32_bf16 v[124:127], v[190:193], v[198:201], v[124:127]
	v_mfma_f32_16x16x32_bf16 v[120:123], v[182:185], v[216:219], v[120:123]
	v_mfma_f32_16x16x32_bf16 v[116:119], v[190:193], v[216:219], v[116:119]
	v_mfma_f32_16x16x32_bf16 v[112:115], v[182:185], v[224:227], v[112:115]
	v_mfma_f32_16x16x32_bf16 v[108:111], v[190:193], v[224:227], v[108:111]
	v_mfma_f32_16x16x32_bf16 v[104:107], v[182:185], v[232:235], v[104:107]
	v_mfma_f32_16x16x32_bf16 v[100:103], v[190:193], v[232:235], v[100:103]
	s_setprio 0
	s_barrier
	s_add_i32 s36, s56, s44
	s_mov_b32 m0, s36
	ds_read_b128 v[194:197], v151 offset:49152
	ds_read_b128 v[198:201], v151 offset:50176
	ds_read_b128 v[212:215], v151 offset:51200
	ds_read_b128 v[216:219], v151 offset:52224
	ds_read_b128 v[220:223], v151 offset:53248
	ds_read_b128 v[224:227], v151 offset:54272
	ds_read_b128 v[228:231], v151 offset:55296
	ds_read_b128 v[232:235], v151 offset:56320
	global_load_lds_dwordx4 v2, s[98:99]
	s_add_i32 m0, s36, 0x2000
	s_add_u32 s26, s26, 0x80080
	s_addc_u32 s27, s27, 0
	s_add_i32 s36, s57, s44
	global_load_lds_dwordx4 v0, s[98:99]
	s_mov_b32 m0, s36
	s_nop 0
	global_load_lds_dwordx4 v2, s[26:27]
	s_add_i32 m0, s36, 0x2000
	s_nop 0
	global_load_lds_dwordx4 v0, s[26:27]
	s_mov_b32 m0, s49
	s_nop 0
	global_load_lds_dwordx4 v134, s[100:101]
	s_mov_b32 m0, s50
	s_nop 0
	global_load_lds_dwordx4 v132, s[100:101]
	s_waitcnt vmcnt(8)
	s_waitcnt lgkmcnt(0)
	s_barrier
	s_setprio 1
	s_waitcnt lgkmcnt(0)
	v_mfma_f32_16x16x32_bf16 v[32:35], v[142:145], v[194:197], v[32:35]
	v_mfma_f32_16x16x32_bf16 v[28:31], v[156:159], v[194:197], v[28:31]
	v_mfma_f32_16x16x32_bf16 v[24:27], v[142:145], v[212:215], v[24:27]
	v_mfma_f32_16x16x32_bf16 v[20:23], v[156:159], v[212:215], v[20:23]
	v_mfma_f32_16x16x32_bf16 v[16:19], v[142:145], v[220:223], v[16:19]
	v_mfma_f32_16x16x32_bf16 v[12:15], v[156:159], v[220:223], v[12:15]
	v_mfma_f32_16x16x32_bf16 v[8:11], v[142:145], v[228:231], v[8:11]
	v_mfma_f32_16x16x32_bf16 v[4:7], v[156:159], v[228:231], v[4:7]
	v_mfma_f32_16x16x32_bf16 v[32:35], v[152:155], v[198:201], v[32:35]
	v_mfma_f32_16x16x32_bf16 v[28:31], v[160:163], v[198:201], v[28:31]
	v_mfma_f32_16x16x32_bf16 v[24:27], v[152:155], v[216:219], v[24:27]
	v_mfma_f32_16x16x32_bf16 v[20:23], v[160:163], v[216:219], v[20:23]
	v_mfma_f32_16x16x32_bf16 v[16:19], v[152:155], v[224:227], v[16:19]
	v_mfma_f32_16x16x32_bf16 v[12:15], v[160:163], v[224:227], v[12:15]
	v_mfma_f32_16x16x32_bf16 v[8:11], v[152:155], v[232:235], v[8:11]
	v_mfma_f32_16x16x32_bf16 v[4:7], v[160:163], v[232:235], v[4:7]
	s_setprio 0
	s_setprio 1
	v_mfma_f32_16x16x32_bf16 v[96:99], v[164:167], v[194:197], v[96:99]
	v_mfma_f32_16x16x32_bf16 v[92:95], v[186:189], v[194:197], v[92:95]
	v_mfma_f32_16x16x32_bf16 v[88:91], v[164:167], v[212:215], v[88:91]
	v_mfma_f32_16x16x32_bf16 v[84:87], v[186:189], v[212:215], v[84:87]
	v_mfma_f32_16x16x32_bf16 v[80:83], v[164:167], v[220:223], v[80:83]
	v_mfma_f32_16x16x32_bf16 v[76:79], v[186:189], v[220:223], v[76:79]
	v_mfma_f32_16x16x32_bf16 v[40:43], v[164:167], v[228:231], v[40:43]
	v_mfma_f32_16x16x32_bf16 v[36:39], v[186:189], v[228:231], v[36:39]
	v_mfma_f32_16x16x32_bf16 v[96:99], v[182:185], v[198:201], v[96:99]
	v_mfma_f32_16x16x32_bf16 v[92:95], v[190:193], v[198:201], v[92:95]
	v_mfma_f32_16x16x32_bf16 v[88:91], v[182:185], v[216:219], v[88:91]
	v_mfma_f32_16x16x32_bf16 v[84:87], v[190:193], v[216:219], v[84:87]
	v_mfma_f32_16x16x32_bf16 v[80:83], v[182:185], v[224:227], v[80:83]
	v_mfma_f32_16x16x32_bf16 v[76:79], v[190:193], v[224:227], v[76:79]
	v_mfma_f32_16x16x32_bf16 v[40:43], v[182:185], v[232:235], v[40:43]
	v_mfma_f32_16x16x32_bf16 v[36:39], v[190:193], v[232:235], v[36:39]
	s_setprio 0
	s_barrier
	s_add_i32 s55, s55, 2
	s_add_u32 s53, s53, 0x100
	s_addc_u32 s54, s54, 0
	s_add_u32 s18, s18, 0x100
	s_addc_u32 s19, s19, 0
	s_cmp_gt_u32 s55, 29
	s_cbranch_scc0 .LBB0_192
	s_and_b64 vcc, exec, s[6:7]
	s_cbranch_vccnz .LBB0_196
	v_lshl_add_u32 v142, s38, 8, v148
	s_cmpk_lg_i32 s33, 0x4a
	s_mov_b64 s[18:19], -1
	s_cbranch_scc1 .LBB0_197

; #define PG8_STAGE(bufoff, gbase, voff) do { _Pragma("unroll") for (int _i = 0; _i < 2; ++_i) \
;         __builtin_amdgcn_global_load_lds((const unsigned*)((const char*)(gbase) + (voff)[_i]), (PG8_LAS unsigned*)(lds + (bufoff) + ldsw + _i * 8192), 16, 0, 0); } while (0)
; #define PG8_LDA(dst, b, h) do { _Pragma("unroll") for (int m = 0; m < 4; ++m) _Pragma("unroll") for (int k = 0; k < 2; ++k) dst[m][k] = *(const PG8_LAS bf16x8*)(lds + PG8_SA(b, h) + aoff + m * 2048 + k * 1024); } while (0)
; #define PG8_LDB(dst, b, h) do { _Pragma("unroll") for (int n = 0; n < 2; ++n) _Pragma("unroll") for (int k = 0; k < 2; ++k) dst[n][k] = *(const PG8_LAS bf16x8*)(lds + PG8_SB(b, h) + boff + n * 2048 + k * 1024); } while (0)
; #define PG8_MMA(ai, bj, At, Bt) do { __builtin_amdgcn_s_setprio(1); _Pragma("unroll") for (int m = 0; m < 4; ++m) _Pragma("unroll") for (int n = 0; n < 2; ++n) _Pragma("unroll") for (int k = 0; k < 2; ++k) \
;         acc[ai][bj][m][n] = __builtin_amdgcn_mfma_f32_16x16x32_bf16(Bt[n][k], At[m][k], acc[ai][bj][m][n], 0, 0, 0); __builtin_amdgcn_s_setprio(0); } while (0)
; #define PG8_WAIT_V(n) asm volatile("s_waitcnt vmcnt(" #n ")" ::: "memory")
; #define PG8_WAIT_L(n) asm volatile("s_waitcnt lgkmcnt(" #n ")" ::: "memory")
; template <class Epi, class Sched, bool ALIGN_EPI = false, bool SP2 = false>
; __device__ __forceinline__ void gemm_phase(PG8_LAS unsigned char* lds, const Gemm g, const Sched& S, const Epi& E, int wave_s) {
;     ...
;             const bool last = (t == nt - 2);
;             const char* a1 = cA + (size_t)(t + 1) * kstep;
;             const char* a2 = last ? nA : cA + (size_t)(t + 2) * kstep; const char* b2 = last ? nB : cB + (size_t)(t + 2) * kstep;
;             const char* a3 = a2 + kstep; const char* b3 = b2 + kstep;
;             if (last && has_next) S.a_ready(nxt);
;             if constexpr (SP2) {
;             PG8_LDB(B0, 0, 0); PG8_LDB(B1, 0, 1); PG8_SCHED; PG8_LDA(At, 0, 0); PG8_STAGE(PG8_SA(1, 1), a1 + hstepA, voffA);
;             PG8_WAIT_V(8); PG8_WAIT_L(0); PG8_BAR; PG8_MMA(0, 0, At, B0); PG8_MMA(0, 1, At, B1); PG8_BAR; PG8_SCHED;
;             PG8_LDA(At, 0, 1); PG8_STAGE(PG8_SB(0, 0), b2, voffB); PG8_STAGE(PG8_SB(0, 1), b2 + hstepB, voffB); PG8_STAGE(PG8_SA(0, 0), a2, voffA);
;             PG8_WAIT_V(8); PG8_WAIT_L(0); PG8_BAR; PG8_MMA(1, 0, At, B0); PG8_MMA(1, 1, At, B1); PG8_BAR; PG8_SCHED;
.LBB0_568:
	s_nop 0
	s_add_u32 s26, s24, 0x100
	s_addc_u32 s27, s25, 0
	s_add_i32 s74, 0, 0x10000
	s_cmp_eq_u32 s67, 4
	s_cselect_b32 s43, s21, s27
	s_cselect_b32 s42, s20, s26
	s_cselect_b32 s39, s19, s66
	s_cselect_b32 s38, s58, s59
	s_add_i32 s75, 0, 0x14000
	ds_read_b128 v[132:135], v255
	ds_read_b128 v[136:139], v255 offset:1024
	ds_read_b128 v[140:143], v255 offset:2048
	ds_read_b128 v[144:147], v255 offset:3072
	ds_read_b128 v[148:151], v255 offset:16384
	ds_read_b128 v[160:163], v255 offset:17408
	ds_read_b128 v[164:167], v255 offset:18432
	ds_read_b128 v[182:185], v255 offset:19456
	v_lshl_add_u64 v[232:233], s[24:25], 0, v[158:159]
	s_add_i32 m0, s49, 0xc000
	ds_read_b128 v[190:193], v188
	ds_read_b128 v[194:197], v188 offset:1024
	ds_read_b128 v[198:201], v188 offset:2048
	ds_read_b128 v[212:215], v188 offset:3072
	ds_read_b128 v[216:219], v188 offset:4096
	ds_read_b128 v[220:223], v188 offset:5120
	ds_read_b128 v[224:227], v188 offset:6144
	ds_read_b128 v[228:231], v188 offset:7168
	global_load_lds_dwordx4 v[232:233], off
	v_lshl_add_u64 v[232:233], s[24:25], 0, v[156:157]
	s_add_i32 m0, s49, 0xe000
	s_nop 0
	global_load_lds_dwordx4 v[232:233], off
	s_waitcnt vmcnt(8)
	s_waitcnt lgkmcnt(0)
	s_barrier
	s_setprio 1
	s_waitcnt lgkmcnt(0)
	v_mfma_f32_16x16x32_bf16 v[128:131], v[132:135], v[190:193], v[128:131]
	v_mfma_f32_16x16x32_bf16 v[124:127], v[140:143], v[190:193], v[124:127]
	v_mfma_f32_16x16x32_bf16 v[120:123], v[132:135], v[198:201], v[120:123]
	v_mfma_f32_16x16x32_bf16 v[112:115], v[140:143], v[198:201], v[112:115]
	v_mfma_f32_16x16x32_bf16 v[100:103], v[132:135], v[216:219], v[100:103]
	v_mfma_f32_16x16x32_bf16 v[92:95], v[140:143], v[216:219], v[92:95]
	v_mfma_f32_16x16x32_bf16 v[84:87], v[132:135], v[224:227], v[84:87]
	v_mfma_f32_16x16x32_bf16 v[76:79], v[140:143], v[224:227], v[76:79]
	v_mfma_f32_16x16x32_bf16 v[128:131], v[136:139], v[194:197], v[128:131]
	v_mfma_f32_16x16x32_bf16 v[124:127], v[144:147], v[194:197], v[124:127]
	v_mfma_f32_16x16x32_bf16 v[120:123], v[136:139], v[212:215], v[120:123]
	v_mfma_f32_16x16x32_bf16 v[112:115], v[144:147], v[212:215], v[112:115]
	v_mfma_f32_16x16x32_bf16 v[100:103], v[136:139], v[220:223], v[100:103]
	v_mfma_f32_16x16x32_bf16 v[92:95], v[144:147], v[220:223], v[92:95]
	v_mfma_f32_16x16x32_bf16 v[84:87], v[136:139], v[228:231], v[84:87]
	v_mfma_f32_16x16x32_bf16 v[76:79], v[144:147], v[228:231], v[76:79]
	s_setprio 0
	s_setprio 1
	v_mfma_f32_16x16x32_bf16 v[116:119], v[148:151], v[190:193], v[116:119]
	v_mfma_f32_16x16x32_bf16 v[108:111], v[164:167], v[190:193], v[108:111]
	v_mfma_f32_16x16x32_bf16 v[104:107], v[148:151], v[198:201], v[104:107]
	v_mfma_f32_16x16x32_bf16 v[96:99], v[164:167], v[198:201], v[96:99]
	v_mfma_f32_16x16x32_bf16 v[88:91], v[148:151], v[216:219], v[88:91]
	v_mfma_f32_16x16x32_bf16 v[80:83], v[164:167], v[216:219], v[80:83]
	v_mfma_f32_16x16x32_bf16 v[72:75], v[148:151], v[224:227], v[72:75]
	v_mfma_f32_16x16x32_bf16 v[68:71], v[164:167], v[224:227], v[68:71]
	v_mfma_f32_16x16x32_bf16 v[116:119], v[160:163], v[194:197], v[116:119]
	v_mfma_f32_16x16x32_bf16 v[108:111], v[182:185], v[194:197], v[108:111]
	v_mfma_f32_16x16x32_bf16 v[104:107], v[160:163], v[212:215], v[104:107]
	v_mfma_f32_16x16x32_bf16 v[96:99], v[182:185], v[212:215], v[96:99]
	v_mfma_f32_16x16x32_bf16 v[88:91], v[160:163], v[220:223], v[88:91]
	v_mfma_f32_16x16x32_bf16 v[80:83], v[182:185], v[220:223], v[80:83]
	v_mfma_f32_16x16x32_bf16 v[72:75], v[160:163], v[228:231], v[72:75]
	v_mfma_f32_16x16x32_bf16 v[68:71], v[182:185], v[228:231], v[68:71]
	s_setprio 0
	s_barrier
	s_add_i32 s24, s74, s48
	s_add_u32 s98, s38, s60
	s_addc_u32 s99, s39, s61
	s_mov_b32 m0, s24
	ds_read_b128 v[190:193], v188 offset:16384
	ds_read_b128 v[194:197], v188 offset:17408
	ds_read_b128 v[198:201], v188 offset:18432
	ds_read_b128 v[212:215], v188 offset:19456
	ds_read_b128 v[216:219], v188 offset:20480
	ds_read_b128 v[220:223], v188 offset:21504
	ds_read_b128 v[224:227], v188 offset:22528
	ds_read_b128 v[228:231], v188 offset:23552
	global_load_lds_dwordx4 v2, s[38:39]
	s_add_i32 m0, s24, 0x2000
	s_add_u32 s24, s38, 0x20000
	s_addc_u32 s25, s39, 0
	s_add_i32 s74, s75, s48
	global_load_lds_dwordx4 v0, s[38:39]
	s_mov_b32 m0, s74
	s_add_u32 s100, s42, s60
	s_addc_u32 s101, s43, s61
	s_nop 0
	global_load_lds_dwordx4 v2, s[24:25]
	s_add_i32 m0, s74, 0x2000
	s_nop 0
	global_load_lds_dwordx4 v0, s[24:25]
	s_mov_b32 m0, s49
	s_nop 0
	global_load_lds_dwordx4 v154, s[42:43]
	s_mov_b32 m0, s50
	s_nop 0
	global_load_lds_dwordx4 v152, s[42:43]
	s_waitcnt vmcnt(8)
	s_waitcnt lgkmcnt(0)
	s_barrier
; #define PG8_STAGE(bufoff, gbase, voff) do { _Pragma("unroll") for (int _i = 0; _i < 2; ++_i) \
;         __builtin_amdgcn_global_load_lds((const unsigned*)((const char*)(gbase) + (voff)[_i]), (PG8_LAS unsigned*)(lds + (bufoff) + ldsw + _i * 8192), 16, 0, 0); } while (0)
; #define PG8_LDA(dst, b, h) do { _Pragma("unroll") for (int m = 0; m < 4; ++m) _Pragma("unroll") for (int k = 0; k < 2; ++k) dst[m][k] = *(const PG8_LAS bf16x8*)(lds + PG8_SA(b, h) + aoff + m * 2048 + k * 1024); } while (0)
; #define PG8_LDB(dst, b, h) do { _Pragma("unroll") for (int n = 0; n < 2; ++n) _Pragma("unroll") for (int k = 0; k < 2; ++k) dst[n][k] = *(const PG8_LAS bf16x8*)(lds + PG8_SB(b, h) + boff + n * 2048 + k * 1024); } while (0)
; #define PG8_MMA(ai, bj, At, Bt) do { __builtin_amdgcn_s_setprio(1); _Pragma("unroll") for (int m = 0; m < 4; ++m) _Pragma("unroll") for (int n = 0; n < 2; ++n) _Pragma("unroll") for (int k = 0; k < 2; ++k) \
;         acc[ai][bj][m][n] = __builtin_amdgcn_mfma_f32_16x16x32_bf16(Bt[n][k], At[m][k], acc[ai][bj][m][n], 0, 0, 0); __builtin_amdgcn_s_setprio(0); } while (0)
; #define PG8_WAIT_V(n) asm volatile("s_waitcnt vmcnt(" #n ")" ::: "memory")
; #define PG8_WAIT_L(n) asm volatile("s_waitcnt lgkmcnt(" #n ")" ::: "memory")
; #define PG8_BAR __builtin_amdgcn_s_barrier()
; #define PG8_SCHED __builtin_amdgcn_sched_barrier(0)
; template <class Epi, class Sched, bool ALIGN_EPI = false, bool SP2 = false>
; __device__ __forceinline__ void gemm_phase(PG8_LAS unsigned char* lds, const Gemm g, const Sched& S, const Epi& E, int wave_s) {
;     ...
;             PG8_WAIT_V(8); PG8_WAIT_L(0); PG8_BAR; PG8_MMA(1, 0, At, B0); PG8_MMA(1, 1, At, B1); PG8_BAR; PG8_SCHED;
;             PG8_LDB(B0, 1, 0); PG8_LDB(B1, 1, 1); PG8_SCHED; PG8_LDA(At, 1, 0); PG8_STAGE(PG8_SA(0, 1), a2 + hstepA, voffA);
;             PG8_WAIT_V(8); PG8_WAIT_L(0); PG8_BAR; PG8_MMA(0, 0, At, B0); PG8_MMA(0, 1, At, B1); PG8_BAR; PG8_SCHED;
	s_setprio 1
	s_waitcnt lgkmcnt(0)
	v_mfma_f32_16x16x32_bf16 v[64:67], v[132:135], v[190:193], v[64:67]
	v_mfma_f32_16x16x32_bf16 v[60:63], v[140:143], v[190:193], v[60:63]
	v_mfma_f32_16x16x32_bf16 v[52:55], v[132:135], v[198:201], v[52:55]
	v_mfma_f32_16x16x32_bf16 v[44:47], v[140:143], v[198:201], v[44:47]
	v_mfma_f32_16x16x32_bf16 v[36:39], v[132:135], v[216:219], v[36:39]
	v_mfma_f32_16x16x32_bf16 v[28:31], v[140:143], v[216:219], v[28:31]
	v_mfma_f32_16x16x32_bf16 v[20:23], v[132:135], v[224:227], v[20:23]
	v_mfma_f32_16x16x32_bf16 v[12:15], v[140:143], v[224:227], v[12:15]
	v_mfma_f32_16x16x32_bf16 v[64:67], v[136:139], v[194:197], v[64:67]
	v_mfma_f32_16x16x32_bf16 v[60:63], v[144:147], v[194:197], v[60:63]
	v_mfma_f32_16x16x32_bf16 v[52:55], v[136:139], v[212:215], v[52:55]
	v_mfma_f32_16x16x32_bf16 v[44:47], v[144:147], v[212:215], v[44:47]
	v_mfma_f32_16x16x32_bf16 v[36:39], v[136:139], v[220:223], v[36:39]
	v_mfma_f32_16x16x32_bf16 v[28:31], v[144:147], v[220:223], v[28:31]
	v_mfma_f32_16x16x32_bf16 v[20:23], v[136:139], v[228:231], v[20:23]
	v_mfma_f32_16x16x32_bf16 v[12:15], v[144:147], v[228:231], v[12:15]
	s_setprio 0
	s_setprio 1
	v_mfma_f32_16x16x32_bf16 v[56:59], v[148:151], v[190:193], v[56:59]
	v_mfma_f32_16x16x32_bf16 v[48:51], v[164:167], v[190:193], v[48:51]
	v_mfma_f32_16x16x32_bf16 v[40:43], v[148:151], v[198:201], v[40:43]
	v_mfma_f32_16x16x32_bf16 v[32:35], v[164:167], v[198:201], v[32:35]
	v_mfma_f32_16x16x32_bf16 v[24:27], v[148:151], v[216:219], v[24:27]
	v_mfma_f32_16x16x32_bf16 v[16:19], v[164:167], v[216:219], v[16:19]
	v_mfma_f32_16x16x32_bf16 v[8:11], v[148:151], v[224:227], v[8:11]
	v_mfma_f32_16x16x32_bf16 v[4:7], v[164:167], v[224:227], v[4:7]
	v_mfma_f32_16x16x32_bf16 v[56:59], v[160:163], v[194:197], v[56:59]
	v_mfma_f32_16x16x32_bf16 v[48:51], v[182:185], v[194:197], v[48:51]
	v_mfma_f32_16x16x32_bf16 v[40:43], v[160:163], v[212:215], v[40:43]
	v_mfma_f32_16x16x32_bf16 v[32:35], v[182:185], v[212:215], v[32:35]
	v_mfma_f32_16x16x32_bf16 v[24:27], v[160:163], v[220:223], v[24:27]
	v_mfma_f32_16x16x32_bf16 v[16:19], v[182:185], v[220:223], v[16:19]
	v_mfma_f32_16x16x32_bf16 v[8:11], v[160:163], v[228:231], v[8:11]
	v_mfma_f32_16x16x32_bf16 v[4:7], v[182:185], v[228:231], v[4:7]
	s_setprio 0
	s_barrier
	s_nop 0
	s_add_i32 s74, 0, 0x18000
	s_add_i32 s75, 0, 0x1c000
	ds_read_b128 v[132:135], v255 offset:32768
	ds_read_b128 v[136:139], v255 offset:33792
	ds_read_b128 v[140:143], v255 offset:34816
	ds_read_b128 v[144:147], v255 offset:35840
	ds_read_b128 v[148:151], v255 offset:49152
	ds_read_b128 v[160:163], v255 offset:50176
	ds_read_b128 v[164:167], v255 offset:51200
	ds_read_b128 v[182:185], v255 offset:52224
	s_add_u32 s24, s42, 0x4b0000
	s_addc_u32 s25, s43, 0
	s_mov_b32 m0, s51
	ds_read_b128 v[190:193], v188 offset:32768
	ds_read_b128 v[194:197], v188 offset:33792
	ds_read_b128 v[198:201], v188 offset:34816
	ds_read_b128 v[212:215], v188 offset:35840
	ds_read_b128 v[216:219], v188 offset:36864
	ds_read_b128 v[220:223], v188 offset:37888
	ds_read_b128 v[224:227], v188 offset:38912
	ds_read_b128 v[228:231], v188 offset:39936
	global_load_lds_dwordx4 v154, s[24:25]
	s_mov_b32 m0, s52
	s_nop 0
	global_load_lds_dwordx4 v152, s[24:25]
	s_waitcnt vmcnt(8)
	s_waitcnt lgkmcnt(0)
	s_barrier
	s_setprio 1
	s_waitcnt lgkmcnt(0)
	v_mfma_f32_16x16x32_bf16 v[128:131], v[132:135], v[190:193], v[128:131]
	v_mfma_f32_16x16x32_bf16 v[124:127], v[140:143], v[190:193], v[124:127]
	v_mfma_f32_16x16x32_bf16 v[120:123], v[132:135], v[198:201], v[120:123]
	v_mfma_f32_16x16x32_bf16 v[112:115], v[140:143], v[198:201], v[112:115]
	v_mfma_f32_16x16x32_bf16 v[100:103], v[132:135], v[216:219], v[100:103]
	v_mfma_f32_16x16x32_bf16 v[92:95], v[140:143], v[216:219], v[92:95]
	v_mfma_f32_16x16x32_bf16 v[84:87], v[132:135], v[224:227], v[84:87]
	v_mfma_f32_16x16x32_bf16 v[76:79], v[140:143], v[224:227], v[76:79]
	v_mfma_f32_16x16x32_bf16 v[128:131], v[136:139], v[194:197], v[128:131]
	v_mfma_f32_16x16x32_bf16 v[124:127], v[144:147], v[194:197], v[124:127]
	v_mfma_f32_16x16x32_bf16 v[120:123], v[136:139], v[212:215], v[120:123]
	v_mfma_f32_16x16x32_bf16 v[112:115], v[144:147], v[212:215], v[112:115]
	v_mfma_f32_16x16x32_bf16 v[100:103], v[136:139], v[220:223], v[100:103]
	v_mfma_f32_16x16x32_bf16 v[92:95], v[144:147], v[220:223], v[92:95]
	v_mfma_f32_16x16x32_bf16 v[84:87], v[136:139], v[228:231], v[84:87]
	v_mfma_f32_16x16x32_bf16 v[76:79], v[144:147], v[228:231], v[76:79]
	s_setprio 0
	s_setprio 1
	v_mfma_f32_16x16x32_bf16 v[116:119], v[148:151], v[190:193], v[116:119]
	v_mfma_f32_16x16x32_bf16 v[108:111], v[164:167], v[190:193], v[108:111]
	v_mfma_f32_16x16x32_bf16 v[104:107], v[148:151], v[198:201], v[104:107]
	v_mfma_f32_16x16x32_bf16 v[96:99], v[164:167], v[198:201], v[96:99]
	v_mfma_f32_16x16x32_bf16 v[88:91], v[148:151], v[216:219], v[88:91]
	v_mfma_f32_16x16x32_bf16 v[80:83], v[164:167], v[216:219], v[80:83]
	v_mfma_f32_16x16x32_bf16 v[72:75], v[148:151], v[224:227], v[72:75]
	v_mfma_f32_16x16x32_bf16 v[68:71], v[164:167], v[224:227], v[68:71]
	v_mfma_f32_16x16x32_bf16 v[116:119], v[160:163], v[194:197], v[116:119]
	v_mfma_f32_16x16x32_bf16 v[108:111], v[182:185], v[194:197], v[108:111]
	v_mfma_f32_16x16x32_bf16 v[104:107], v[160:163], v[212:215], v[104:107]
	v_mfma_f32_16x16x32_bf16 v[96:99], v[182:185], v[212:215], v[96:99]
	v_mfma_f32_16x16x32_bf16 v[88:91], v[160:163], v[220:223], v[88:91]
	v_mfma_f32_16x16x32_bf16 v[80:83], v[182:185], v[220:223], v[80:83]
	v_mfma_f32_16x16x32_bf16 v[72:75], v[160:163], v[228:231], v[72:75]
	v_mfma_f32_16x16x32_bf16 v[68:71], v[182:185], v[228:231], v[68:71]
	s_setprio 0
	s_barrier
; #define PG8_STAGE(bufoff, gbase, voff) do { _Pragma("unroll") for (int _i = 0; _i < 2; ++_i) \
;         __builtin_amdgcn_global_load_lds((const unsigned*)((const char*)(gbase) + (voff)[_i]), (PG8_LAS unsigned*)(lds + (bufoff) + ldsw + _i * 8192), 16, 0, 0); } while (0)
; #define PG8_LDA(dst, b, h) do { _Pragma("unroll") for (int m = 0; m < 4; ++m) _Pragma("unroll") for (int k = 0; k < 2; ++k) dst[m][k] = *(const PG8_LAS bf16x8*)(lds + PG8_SA(b, h) + aoff + m * 2048 + k * 1024); } while (0)
; #define PG8_MMA(ai, bj, At, Bt) do { __builtin_amdgcn_s_setprio(1); _Pragma("unroll") for (int m = 0; m < 4; ++m) _Pragma("unroll") for (int n = 0; n < 2; ++n) _Pragma("unroll") for (int k = 0; k < 2; ++k) \
;         acc[ai][bj][m][n] = __builtin_amdgcn_mfma_f32_16x16x32_bf16(Bt[n][k], At[m][k], acc[ai][bj][m][n], 0, 0, 0); __builtin_amdgcn_s_setprio(0); } while (0)
; #define PG8_WAIT_V(n) asm volatile("s_waitcnt vmcnt(" #n ")" ::: "memory")
; #define PG8_WAIT_L(n) asm volatile("s_waitcnt lgkmcnt(" #n ")" ::: "memory")
; #define PG8_BAR __builtin_amdgcn_s_barrier()
; #define PG8_SCHED __builtin_amdgcn_sched_barrier(0)
; template <class Epi, class Sched, bool ALIGN_EPI = false, bool SP2 = false>
; __device__ __forceinline__ void gemm_phase(PG8_LAS unsigned char* lds, const Gemm g, const Sched& S, const Epi& E, int wave_s) {
;     ...
;             PG8_LDA(At, 1, 1); PG8_STAGE(PG8_SB(1, 0), b3, voffB); PG8_STAGE(PG8_SB(1, 1), b3 + hstepB, voffB); PG8_STAGE(PG8_SA(1, 0), a3, voffA);
;             PG8_WAIT_V(8); PG8_WAIT_L(0); PG8_BAR; PG8_MMA(1, 0, At, B0); PG8_MMA(1, 1, At, B1); PG8_BAR; PG8_SCHED;
	s_add_i32 s24, s74, s48
	s_mov_b32 m0, s24
	ds_read_b128 v[190:193], v188 offset:49152
	ds_read_b128 v[194:197], v188 offset:50176
	ds_read_b128 v[198:201], v188 offset:51200
	ds_read_b128 v[212:215], v188 offset:52224
	ds_read_b128 v[216:219], v188 offset:53248
	ds_read_b128 v[220:223], v188 offset:54272
	ds_read_b128 v[224:227], v188 offset:55296
	ds_read_b128 v[228:231], v188 offset:56320
	global_load_lds_dwordx4 v2, s[98:99]
	s_add_i32 m0, s24, 0x2000
	s_add_u32 s24, s38, 0x20080
	s_addc_u32 s25, s39, 0
	s_add_i32 s38, s75, s48
	global_load_lds_dwordx4 v0, s[98:99]
	s_mov_b32 m0, s38
	s_nop 0
	global_load_lds_dwordx4 v2, s[24:25]
	s_add_i32 m0, s38, 0x2000
	s_nop 0
	global_load_lds_dwordx4 v0, s[24:25]
	s_mov_b32 m0, s53
	s_nop 0
	global_load_lds_dwordx4 v154, s[100:101]
	s_mov_b32 m0, s54
	s_nop 0
	global_load_lds_dwordx4 v152, s[100:101]
	s_waitcnt vmcnt(8)
	s_waitcnt lgkmcnt(0)
	s_barrier
	s_setprio 1
	s_waitcnt lgkmcnt(0)
	v_mfma_f32_16x16x32_bf16 v[64:67], v[132:135], v[190:193], v[64:67]
	v_mfma_f32_16x16x32_bf16 v[60:63], v[140:143], v[190:193], v[60:63]
	v_mfma_f32_16x16x32_bf16 v[52:55], v[132:135], v[198:201], v[52:55]
	v_mfma_f32_16x16x32_bf16 v[44:47], v[140:143], v[198:201], v[44:47]
	v_mfma_f32_16x16x32_bf16 v[36:39], v[132:135], v[216:219], v[36:39]
	v_mfma_f32_16x16x32_bf16 v[28:31], v[140:143], v[216:219], v[28:31]
	v_mfma_f32_16x16x32_bf16 v[20:23], v[132:135], v[224:227], v[20:23]
	v_mfma_f32_16x16x32_bf16 v[12:15], v[140:143], v[224:227], v[12:15]
	v_mfma_f32_16x16x32_bf16 v[64:67], v[136:139], v[194:197], v[64:67]
	v_mfma_f32_16x16x32_bf16 v[60:63], v[144:147], v[194:197], v[60:63]
	v_mfma_f32_16x16x32_bf16 v[52:55], v[136:139], v[212:215], v[52:55]
	v_mfma_f32_16x16x32_bf16 v[44:47], v[144:147], v[212:215], v[44:47]
	v_mfma_f32_16x16x32_bf16 v[36:39], v[136:139], v[220:223], v[36:39]
	v_mfma_f32_16x16x32_bf16 v[28:31], v[144:147], v[220:223], v[28:31]
	v_mfma_f32_16x16x32_bf16 v[20:23], v[136:139], v[228:231], v[20:23]
	v_mfma_f32_16x16x32_bf16 v[12:15], v[144:147], v[228:231], v[12:15]
	s_setprio 0
	s_setprio 1
	v_mfma_f32_16x16x32_bf16 v[56:59], v[148:151], v[190:193], v[56:59]
	v_mfma_f32_16x16x32_bf16 v[48:51], v[164:167], v[190:193], v[48:51]
	v_mfma_f32_16x16x32_bf16 v[40:43], v[148:151], v[198:201], v[40:43]
	v_mfma_f32_16x16x32_bf16 v[32:35], v[164:167], v[198:201], v[32:35]
	v_mfma_f32_16x16x32_bf16 v[24:27], v[148:151], v[216:219], v[24:27]
	v_mfma_f32_16x16x32_bf16 v[16:19], v[164:167], v[216:219], v[16:19]
	v_mfma_f32_16x16x32_bf16 v[8:11], v[148:151], v[224:227], v[8:11]
	v_mfma_f32_16x16x32_bf16 v[4:7], v[164:167], v[224:227], v[4:7]
	v_mfma_f32_16x16x32_bf16 v[56:59], v[160:163], v[194:197], v[56:59]
	v_mfma_f32_16x16x32_bf16 v[48:51], v[182:185], v[194:197], v[48:51]
	v_mfma_f32_16x16x32_bf16 v[40:43], v[160:163], v[212:215], v[40:43]
	v_mfma_f32_16x16x32_bf16 v[32:35], v[182:185], v[212:215], v[32:35]
	v_mfma_f32_16x16x32_bf16 v[24:27], v[160:163], v[220:223], v[24:27]
	v_mfma_f32_16x16x32_bf16 v[16:19], v[182:185], v[220:223], v[16:19]
	v_mfma_f32_16x16x32_bf16 v[8:11], v[160:163], v[228:231], v[8:11]
	v_mfma_f32_16x16x32_bf16 v[4:7], v[182:185], v[228:231], v[4:7]
	s_setprio 0
	s_barrier
	s_add_i32 s67, s67, 2
	s_add_u32 s59, s59, 0x100
	s_addc_u32 s66, s66, 0
	s_cmp_gt_u32 s67, 5
	s_mov_b64 s[24:25], s[26:27]
	s_cbranch_scc0 .LBB0_568
	s_and_b64 vcc, exec, s[16:17]
	s_cbranch_vccz .LBB0_571
	s_barrier

; #define PG8_STAGE(bufoff, gbase, voff) do { _Pragma("unroll") for (int _i = 0; _i < 2; ++_i) \
;         __builtin_amdgcn_global_load_lds((const unsigned*)((const char*)(gbase) + (voff)[_i]), (PG8_LAS unsigned*)(lds + (bufoff) + ldsw + _i * 8192), 16, 0, 0); } while (0)
; #define PG8_LDA(dst, b, h) do { _Pragma("unroll") for (int m = 0; m < 4; ++m) _Pragma("unroll") for (int k = 0; k < 2; ++k) dst[m][k] = *(const PG8_LAS bf16x8*)(lds + PG8_SA(b, h) + aoff + m * 2048 + k * 1024); } while (0)
; #define PG8_LDB(dst, b, h) do { _Pragma("unroll") for (int n = 0; n < 2; ++n) _Pragma("unroll") for (int k = 0; k < 2; ++k) dst[n][k] = *(const PG8_LAS bf16x8*)(lds + PG8_SB(b, h) + boff + n * 2048 + k * 1024); } while (0)
; #define PG8_MMA(ai, bj, At, Bt) do { __builtin_amdgcn_s_setprio(1); _Pragma("unroll") for (int m = 0; m < 4; ++m) _Pragma("unroll") for (int n = 0; n < 2; ++n) _Pragma("unroll") for (int k = 0; k < 2; ++k) \
;         acc[ai][bj][m][n] = __builtin_amdgcn_mfma_f32_16x16x32_bf16(Bt[n][k], At[m][k], acc[ai][bj][m][n], 0, 0, 0); __builtin_amdgcn_s_setprio(0); } while (0)
; #define PG8_WAIT_V(n) asm volatile("s_waitcnt vmcnt(" #n ")" ::: "memory")
; #define PG8_WAIT_L(n) asm volatile("s_waitcnt lgkmcnt(" #n ")" ::: "memory")
; template <class Epi, class Sched, bool ALIGN_EPI = false, bool SP2 = false>
; __device__ __forceinline__ void gemm_phase(PG8_LAS unsigned char* lds, const Gemm g, const Sched& S, const Epi& E, int wave_s) {
;     ...
;             const bool last = (t == nt - 2);
;             const char* a1 = cA + (size_t)(t + 1) * kstep;
;             const char* a2 = last ? nA : cA + (size_t)(t + 2) * kstep; const char* b2 = last ? nB : cB + (size_t)(t + 2) * kstep;
;             const char* a3 = a2 + kstep; const char* b3 = b2 + kstep;
;             if (last && has_next) S.a_ready(nxt);
;             if constexpr (SP2) {
;             PG8_LDB(B0, 0, 0); PG8_LDB(B1, 0, 1); PG8_SCHED; PG8_LDA(At, 0, 0); PG8_STAGE(PG8_SA(1, 1), a1 + hstepA, voffA);
;             PG8_WAIT_V(8); PG8_WAIT_L(0); PG8_BAR; PG8_MMA(0, 0, At, B0); PG8_MMA(0, 1, At, B1); PG8_BAR; PG8_SCHED;
;             PG8_LDA(At, 0, 1); PG8_STAGE(PG8_SB(0, 0), b2, voffB); PG8_STAGE(PG8_SB(0, 1), b2 + hstepB, voffB); PG8_STAGE(PG8_SA(0, 0), a2, voffA);
;             PG8_WAIT_V(8); PG8_WAIT_L(0); PG8_BAR; PG8_MMA(1, 0, At, B0); PG8_MMA(1, 1, At, B1); PG8_BAR; PG8_SCHED;
.LBB0_590:
	s_add_u32 s0, s4, 0x100
	s_addc_u32 s1, s5, 0
	s_add_i32 s58, 0, 0x10000
	s_cmp_eq_u32 s57, 60
	s_cselect_b32 s17, s49, s1
	s_cselect_b32 s16, s48, s0
	s_cselect_b32 s7, s38, s56
	s_cselect_b32 s6, s39, s47
	s_add_i32 s59, 0, 0x14000
	ds_read_b128 v[100:103], v255
	ds_read_b128 v[120:123], v255 offset:1024
	ds_read_b128 v[124:127], v255 offset:2048
	ds_read_b128 v[144:147], v255 offset:3072
	ds_read_b128 v[148:151], v255 offset:16384
	ds_read_b128 v[152:155], v255 offset:17408
	ds_read_b128 v[156:159], v255 offset:18432
	ds_read_b128 v[182:185], v255 offset:19456
	v_lshl_add_u64 v[232:233], s[4:5], 0, v[166:167]
	s_add_i32 m0, s25, 0xc000
	ds_read_b128 v[186:189], v196
	ds_read_b128 v[190:193], v196 offset:1024
	ds_read_b128 v[198:201], v196 offset:2048
	ds_read_b128 v[212:215], v196 offset:3072
	ds_read_b128 v[216:219], v196 offset:4096
	ds_read_b128 v[220:223], v196 offset:5120
	ds_read_b128 v[224:227], v196 offset:6144
	ds_read_b128 v[228:231], v196 offset:7168
	global_load_lds_dwordx4 v[232:233], off
	v_lshl_add_u64 v[232:233], s[4:5], 0, v[164:165]
	s_add_i32 m0, s25, 0xe000
	s_nop 0
	global_load_lds_dwordx4 v[232:233], off
	s_waitcnt vmcnt(8)
	s_waitcnt lgkmcnt(0)
	s_barrier
	s_setprio 1
	s_waitcnt lgkmcnt(0)
	v_mfma_f32_16x16x32_bf16 v[140:143], v[100:103], v[186:189], v[140:143]
	v_mfma_f32_16x16x32_bf16 v[136:139], v[124:127], v[186:189], v[136:139]
	v_mfma_f32_16x16x32_bf16 v[116:119], v[100:103], v[198:201], v[116:119]
	v_mfma_f32_16x16x32_bf16 v[112:115], v[124:127], v[198:201], v[112:115]
	v_mfma_f32_16x16x32_bf16 v[96:99], v[100:103], v[216:219], v[96:99]
	v_mfma_f32_16x16x32_bf16 v[92:95], v[124:127], v[216:219], v[92:95]
	v_mfma_f32_16x16x32_bf16 v[80:83], v[100:103], v[224:227], v[80:83]
	v_mfma_f32_16x16x32_bf16 v[76:79], v[124:127], v[224:227], v[76:79]
	v_mfma_f32_16x16x32_bf16 v[140:143], v[120:123], v[190:193], v[140:143]
	v_mfma_f32_16x16x32_bf16 v[136:139], v[144:147], v[190:193], v[136:139]
	v_mfma_f32_16x16x32_bf16 v[116:119], v[120:123], v[212:215], v[116:119]
	v_mfma_f32_16x16x32_bf16 v[112:115], v[144:147], v[212:215], v[112:115]
	v_mfma_f32_16x16x32_bf16 v[96:99], v[120:123], v[220:223], v[96:99]
	v_mfma_f32_16x16x32_bf16 v[92:95], v[144:147], v[220:223], v[92:95]
	v_mfma_f32_16x16x32_bf16 v[80:83], v[120:123], v[228:231], v[80:83]
	v_mfma_f32_16x16x32_bf16 v[76:79], v[144:147], v[228:231], v[76:79]
	s_setprio 0
	s_setprio 1
	v_mfma_f32_16x16x32_bf16 v[132:135], v[148:151], v[186:189], v[132:135]
	v_mfma_f32_16x16x32_bf16 v[128:131], v[156:159], v[186:189], v[128:131]
	v_mfma_f32_16x16x32_bf16 v[108:111], v[148:151], v[198:201], v[108:111]
	v_mfma_f32_16x16x32_bf16 v[104:107], v[156:159], v[198:201], v[104:107]
	v_mfma_f32_16x16x32_bf16 v[88:91], v[148:151], v[216:219], v[88:91]
	v_mfma_f32_16x16x32_bf16 v[84:87], v[156:159], v[216:219], v[84:87]
	v_mfma_f32_16x16x32_bf16 v[72:75], v[148:151], v[224:227], v[72:75]
	v_mfma_f32_16x16x32_bf16 v[68:71], v[156:159], v[224:227], v[68:71]
	v_mfma_f32_16x16x32_bf16 v[132:135], v[152:155], v[190:193], v[132:135]
	v_mfma_f32_16x16x32_bf16 v[128:131], v[182:185], v[190:193], v[128:131]
	v_mfma_f32_16x16x32_bf16 v[108:111], v[152:155], v[212:215], v[108:111]
	v_mfma_f32_16x16x32_bf16 v[104:107], v[182:185], v[212:215], v[104:107]
	v_mfma_f32_16x16x32_bf16 v[88:91], v[152:155], v[220:223], v[88:91]
	v_mfma_f32_16x16x32_bf16 v[84:87], v[182:185], v[220:223], v[84:87]
	v_mfma_f32_16x16x32_bf16 v[72:75], v[152:155], v[228:231], v[72:75]
	v_mfma_f32_16x16x32_bf16 v[68:71], v[182:185], v[228:231], v[68:71]
	s_setprio 0
	s_barrier
	s_add_i32 s4, s58, s24
	s_add_u32 s98, s6, s60
	s_addc_u32 s99, s7, s61
	s_mov_b32 m0, s4
	ds_read_b128 v[186:189], v196 offset:16384
	ds_read_b128 v[190:193], v196 offset:17408
	ds_read_b128 v[198:201], v196 offset:18432
	ds_read_b128 v[212:215], v196 offset:19456
	ds_read_b128 v[216:219], v196 offset:20480
	ds_read_b128 v[220:223], v196 offset:21504
	ds_read_b128 v[224:227], v196 offset:22528
	ds_read_b128 v[228:231], v196 offset:23552
	global_load_lds_dwordx4 v2, s[6:7]
	s_add_i32 m0, s4, 0x2000
	s_add_u32 s4, s6, 0x100000
	s_addc_u32 s5, s7, 0
	s_add_i32 s58, s59, s24
	global_load_lds_dwordx4 v0, s[6:7]
	s_mov_b32 m0, s58
	s_add_u32 s100, s16, s60
	s_addc_u32 s101, s17, s61
	s_nop 0
	global_load_lds_dwordx4 v2, s[4:5]
	s_add_i32 m0, s58, 0x2000
	s_nop 0
	global_load_lds_dwordx4 v0, s[4:5]
	s_mov_b32 m0, s25
	s_nop 0
	global_load_lds_dwordx4 v162, s[16:17]
	s_mov_b32 m0, s26
	s_nop 0
	global_load_lds_dwordx4 v160, s[16:17]
	s_waitcnt vmcnt(8)
	s_waitcnt lgkmcnt(0)
	s_barrier
; #define PG8_STAGE(bufoff, gbase, voff) do { _Pragma("unroll") for (int _i = 0; _i < 2; ++_i) \
;         __builtin_amdgcn_global_load_lds((const unsigned*)((const char*)(gbase) + (voff)[_i]), (PG8_LAS unsigned*)(lds + (bufoff) + ldsw + _i * 8192), 16, 0, 0); } while (0)
; #define PG8_LDA(dst, b, h) do { _Pragma("unroll") for (int m = 0; m < 4; ++m) _Pragma("unroll") for (int k = 0; k < 2; ++k) dst[m][k] = *(const PG8_LAS bf16x8*)(lds + PG8_SA(b, h) + aoff + m * 2048 + k * 1024); } while (0)
; #define PG8_LDB(dst, b, h) do { _Pragma("unroll") for (int n = 0; n < 2; ++n) _Pragma("unroll") for (int k = 0; k < 2; ++k) dst[n][k] = *(const PG8_LAS bf16x8*)(lds + PG8_SB(b, h) + boff + n * 2048 + k * 1024); } while (0)
; #define PG8_MMA(ai, bj, At, Bt) do { __builtin_amdgcn_s_setprio(1); _Pragma("unroll") for (int m = 0; m < 4; ++m) _Pragma("unroll") for (int n = 0; n < 2; ++n) _Pragma("unroll") for (int k = 0; k < 2; ++k) \
;         acc[ai][bj][m][n] = __builtin_amdgcn_mfma_f32_16x16x32_bf16(Bt[n][k], At[m][k], acc[ai][bj][m][n], 0, 0, 0); __builtin_amdgcn_s_setprio(0); } while (0)
; #define PG8_WAIT_V(n) asm volatile("s_waitcnt vmcnt(" #n ")" ::: "memory")
; #define PG8_WAIT_L(n) asm volatile("s_waitcnt lgkmcnt(" #n ")" ::: "memory")
; #define PG8_BAR __builtin_amdgcn_s_barrier()
; #define PG8_SCHED __builtin_amdgcn_sched_barrier(0)
; template <class Epi, class Sched, bool ALIGN_EPI = false, bool SP2 = false>
; __device__ __forceinline__ void gemm_phase(PG8_LAS unsigned char* lds, const Gemm g, const Sched& S, const Epi& E, int wave_s) {
;     ...
;             PG8_WAIT_V(8); PG8_WAIT_L(0); PG8_BAR; PG8_MMA(1, 0, At, B0); PG8_MMA(1, 1, At, B1); PG8_BAR; PG8_SCHED;
;             PG8_LDB(B0, 1, 0); PG8_LDB(B1, 1, 1); PG8_SCHED; PG8_LDA(At, 1, 0); PG8_STAGE(PG8_SA(0, 1), a2 + hstepA, voffA);
;             PG8_WAIT_V(8); PG8_WAIT_L(0); PG8_BAR; PG8_MMA(0, 0, At, B0); PG8_MMA(0, 1, At, B1); PG8_BAR; PG8_SCHED;
	s_setprio 1
	s_waitcnt lgkmcnt(0)
	v_mfma_f32_16x16x32_bf16 v[64:67], v[100:103], v[186:189], v[64:67]
	v_mfma_f32_16x16x32_bf16 v[60:63], v[124:127], v[186:189], v[60:63]
	v_mfma_f32_16x16x32_bf16 v[48:51], v[100:103], v[198:201], v[48:51]
	v_mfma_f32_16x16x32_bf16 v[44:47], v[124:127], v[198:201], v[44:47]
	v_mfma_f32_16x16x32_bf16 v[32:35], v[100:103], v[216:219], v[32:35]
	v_mfma_f32_16x16x32_bf16 v[28:31], v[124:127], v[216:219], v[28:31]
	v_mfma_f32_16x16x32_bf16 v[16:19], v[100:103], v[224:227], v[16:19]
	v_mfma_f32_16x16x32_bf16 v[12:15], v[124:127], v[224:227], v[12:15]
	v_mfma_f32_16x16x32_bf16 v[64:67], v[120:123], v[190:193], v[64:67]
	v_mfma_f32_16x16x32_bf16 v[60:63], v[144:147], v[190:193], v[60:63]
	v_mfma_f32_16x16x32_bf16 v[48:51], v[120:123], v[212:215], v[48:51]
	v_mfma_f32_16x16x32_bf16 v[44:47], v[144:147], v[212:215], v[44:47]
	v_mfma_f32_16x16x32_bf16 v[32:35], v[120:123], v[220:223], v[32:35]
	v_mfma_f32_16x16x32_bf16 v[28:31], v[144:147], v[220:223], v[28:31]
	v_mfma_f32_16x16x32_bf16 v[16:19], v[120:123], v[228:231], v[16:19]
	v_mfma_f32_16x16x32_bf16 v[12:15], v[144:147], v[228:231], v[12:15]
	s_setprio 0
	s_setprio 1
	v_mfma_f32_16x16x32_bf16 v[56:59], v[148:151], v[186:189], v[56:59]
	v_mfma_f32_16x16x32_bf16 v[52:55], v[156:159], v[186:189], v[52:55]
	v_mfma_f32_16x16x32_bf16 v[40:43], v[148:151], v[198:201], v[40:43]
	v_mfma_f32_16x16x32_bf16 v[36:39], v[156:159], v[198:201], v[36:39]
	v_mfma_f32_16x16x32_bf16 v[24:27], v[148:151], v[216:219], v[24:27]
	v_mfma_f32_16x16x32_bf16 v[20:23], v[156:159], v[216:219], v[20:23]
	v_mfma_f32_16x16x32_bf16 v[8:11], v[148:151], v[224:227], v[8:11]
	v_mfma_f32_16x16x32_bf16 v[4:7], v[156:159], v[224:227], v[4:7]
	v_mfma_f32_16x16x32_bf16 v[56:59], v[152:155], v[190:193], v[56:59]
	v_mfma_f32_16x16x32_bf16 v[52:55], v[182:185], v[190:193], v[52:55]
	v_mfma_f32_16x16x32_bf16 v[40:43], v[152:155], v[212:215], v[40:43]
	v_mfma_f32_16x16x32_bf16 v[36:39], v[182:185], v[212:215], v[36:39]
	v_mfma_f32_16x16x32_bf16 v[24:27], v[152:155], v[220:223], v[24:27]
	v_mfma_f32_16x16x32_bf16 v[20:23], v[182:185], v[220:223], v[20:23]
	v_mfma_f32_16x16x32_bf16 v[8:11], v[152:155], v[228:231], v[8:11]
	v_mfma_f32_16x16x32_bf16 v[4:7], v[182:185], v[228:231], v[4:7]
	s_setprio 0
	s_barrier
	s_nop 0
	s_add_i32 s58, 0, 0x18000
	s_add_i32 s59, 0, 0x1c000
	ds_read_b128 v[100:103], v255 offset:32768
	ds_read_b128 v[120:123], v255 offset:33792
	ds_read_b128 v[124:127], v255 offset:34816
	ds_read_b128 v[144:147], v255 offset:35840
	ds_read_b128 v[148:151], v255 offset:49152
	ds_read_b128 v[152:155], v255 offset:50176
	ds_read_b128 v[156:159], v255 offset:51200
	ds_read_b128 v[182:185], v255 offset:52224
	s_add_u32 s4, s16, 0x4b0000
	s_addc_u32 s5, s17, 0
	s_mov_b32 m0, s27
	ds_read_b128 v[186:189], v196 offset:32768
	ds_read_b128 v[190:193], v196 offset:33792
	ds_read_b128 v[198:201], v196 offset:34816
	ds_read_b128 v[212:215], v196 offset:35840
	ds_read_b128 v[216:219], v196 offset:36864
	ds_read_b128 v[220:223], v196 offset:37888
	ds_read_b128 v[224:227], v196 offset:38912
	ds_read_b128 v[228:231], v196 offset:39936
	global_load_lds_dwordx4 v162, s[4:5]
	s_mov_b32 m0, s30
	s_nop 0
	global_load_lds_dwordx4 v160, s[4:5]
	s_waitcnt vmcnt(8)
	s_waitcnt lgkmcnt(0)
	s_barrier
	s_setprio 1
	s_waitcnt lgkmcnt(0)
	v_mfma_f32_16x16x32_bf16 v[140:143], v[100:103], v[186:189], v[140:143]
	v_mfma_f32_16x16x32_bf16 v[136:139], v[124:127], v[186:189], v[136:139]
	v_mfma_f32_16x16x32_bf16 v[116:119], v[100:103], v[198:201], v[116:119]
	v_mfma_f32_16x16x32_bf16 v[112:115], v[124:127], v[198:201], v[112:115]
	v_mfma_f32_16x16x32_bf16 v[96:99], v[100:103], v[216:219], v[96:99]
	v_mfma_f32_16x16x32_bf16 v[92:95], v[124:127], v[216:219], v[92:95]
	v_mfma_f32_16x16x32_bf16 v[80:83], v[100:103], v[224:227], v[80:83]
	v_mfma_f32_16x16x32_bf16 v[76:79], v[124:127], v[224:227], v[76:79]
	v_mfma_f32_16x16x32_bf16 v[140:143], v[120:123], v[190:193], v[140:143]
	v_mfma_f32_16x16x32_bf16 v[136:139], v[144:147], v[190:193], v[136:139]
	v_mfma_f32_16x16x32_bf16 v[116:119], v[120:123], v[212:215], v[116:119]
	v_mfma_f32_16x16x32_bf16 v[112:115], v[144:147], v[212:215], v[112:115]
	v_mfma_f32_16x16x32_bf16 v[96:99], v[120:123], v[220:223], v[96:99]
	v_mfma_f32_16x16x32_bf16 v[92:95], v[144:147], v[220:223], v[92:95]
	v_mfma_f32_16x16x32_bf16 v[80:83], v[120:123], v[228:231], v[80:83]
	v_mfma_f32_16x16x32_bf16 v[76:79], v[144:147], v[228:231], v[76:79]
	s_setprio 0
	s_setprio 1
	v_mfma_f32_16x16x32_bf16 v[132:135], v[148:151], v[186:189], v[132:135]
	v_mfma_f32_16x16x32_bf16 v[128:131], v[156:159], v[186:189], v[128:131]
	v_mfma_f32_16x16x32_bf16 v[108:111], v[148:151], v[198:201], v[108:111]
	v_mfma_f32_16x16x32_bf16 v[104:107], v[156:159], v[198:201], v[104:107]
	v_mfma_f32_16x16x32_bf16 v[88:91], v[148:151], v[216:219], v[88:91]
	v_mfma_f32_16x16x32_bf16 v[84:87], v[156:159], v[216:219], v[84:87]
	v_mfma_f32_16x16x32_bf16 v[72:75], v[148:151], v[224:227], v[72:75]
	v_mfma_f32_16x16x32_bf16 v[68:71], v[156:159], v[224:227], v[68:71]
	v_mfma_f32_16x16x32_bf16 v[132:135], v[152:155], v[190:193], v[132:135]
	v_mfma_f32_16x16x32_bf16 v[128:131], v[182:185], v[190:193], v[128:131]
	v_mfma_f32_16x16x32_bf16 v[108:111], v[152:155], v[212:215], v[108:111]
	v_mfma_f32_16x16x32_bf16 v[104:107], v[182:185], v[212:215], v[104:107]
	v_mfma_f32_16x16x32_bf16 v[88:91], v[152:155], v[220:223], v[88:91]
	v_mfma_f32_16x16x32_bf16 v[84:87], v[182:185], v[220:223], v[84:87]
	v_mfma_f32_16x16x32_bf16 v[72:75], v[152:155], v[228:231], v[72:75]
	v_mfma_f32_16x16x32_bf16 v[68:71], v[182:185], v[228:231], v[68:71]
	s_setprio 0
	s_barrier
; #define PG8_STAGE(bufoff, gbase, voff) do { _Pragma("unroll") for (int _i = 0; _i < 2; ++_i) \
;         __builtin_amdgcn_global_load_lds((const unsigned*)((const char*)(gbase) + (voff)[_i]), (PG8_LAS unsigned*)(lds + (bufoff) + ldsw + _i * 8192), 16, 0, 0); } while (0)
; #define PG8_LDA(dst, b, h) do { _Pragma("unroll") for (int m = 0; m < 4; ++m) _Pragma("unroll") for (int k = 0; k < 2; ++k) dst[m][k] = *(const PG8_LAS bf16x8*)(lds + PG8_SA(b, h) + aoff + m * 2048 + k * 1024); } while (0)
; #define PG8_MMA(ai, bj, At, Bt) do { __builtin_amdgcn_s_setprio(1); _Pragma("unroll") for (int m = 0; m < 4; ++m) _Pragma("unroll") for (int n = 0; n < 2; ++n) _Pragma("unroll") for (int k = 0; k < 2; ++k) \
;         acc[ai][bj][m][n] = __builtin_amdgcn_mfma_f32_16x16x32_bf16(Bt[n][k], At[m][k], acc[ai][bj][m][n], 0, 0, 0); __builtin_amdgcn_s_setprio(0); } while (0)
; #define PG8_WAIT_V(n) asm volatile("s_waitcnt vmcnt(" #n ")" ::: "memory")
; #define PG8_WAIT_L(n) asm volatile("s_waitcnt lgkmcnt(" #n ")" ::: "memory")
; #define PG8_BAR __builtin_amdgcn_s_barrier()
; #define PG8_SCHED __builtin_amdgcn_sched_barrier(0)
; template <class Epi, class Sched, bool ALIGN_EPI = false, bool SP2 = false>
; __device__ __forceinline__ void gemm_phase(PG8_LAS unsigned char* lds, const Gemm g, const Sched& S, const Epi& E, int wave_s) {
;     ...
;             PG8_LDA(At, 1, 1); PG8_STAGE(PG8_SB(1, 0), b3, voffB); PG8_STAGE(PG8_SB(1, 1), b3 + hstepB, voffB); PG8_STAGE(PG8_SA(1, 0), a3, voffA);
;             PG8_WAIT_V(8); PG8_WAIT_L(0); PG8_BAR; PG8_MMA(1, 0, At, B0); PG8_MMA(1, 1, At, B1); PG8_BAR; PG8_SCHED;
	s_add_i32 s4, s58, s24
	s_mov_b32 m0, s4
	ds_read_b128 v[186:189], v196 offset:49152
	ds_read_b128 v[190:193], v196 offset:50176
	ds_read_b128 v[198:201], v196 offset:51200
	ds_read_b128 v[212:215], v196 offset:52224
	ds_read_b128 v[216:219], v196 offset:53248
	ds_read_b128 v[220:223], v196 offset:54272
	ds_read_b128 v[224:227], v196 offset:55296
	ds_read_b128 v[228:231], v196 offset:56320
	global_load_lds_dwordx4 v2, s[98:99]
	s_add_i32 m0, s4, 0x2000
	s_add_u32 s4, s6, 0x100080
	s_addc_u32 s5, s7, 0
	s_add_i32 s6, s59, s24
	global_load_lds_dwordx4 v0, s[98:99]
	s_mov_b32 m0, s6
	s_nop 0
	global_load_lds_dwordx4 v2, s[4:5]
	s_add_i32 m0, s6, 0x2000
	s_nop 0
	global_load_lds_dwordx4 v0, s[4:5]
	s_mov_b32 m0, s52
	s_nop 0
	global_load_lds_dwordx4 v162, s[100:101]
	s_mov_b32 m0, s53
	s_nop 0
	global_load_lds_dwordx4 v160, s[100:101]
	s_waitcnt vmcnt(8)
	s_waitcnt lgkmcnt(0)
	s_barrier
	s_setprio 1
	s_waitcnt lgkmcnt(0)
	v_mfma_f32_16x16x32_bf16 v[64:67], v[100:103], v[186:189], v[64:67]
	v_mfma_f32_16x16x32_bf16 v[60:63], v[124:127], v[186:189], v[60:63]
	v_mfma_f32_16x16x32_bf16 v[48:51], v[100:103], v[198:201], v[48:51]
	v_mfma_f32_16x16x32_bf16 v[44:47], v[124:127], v[198:201], v[44:47]
	v_mfma_f32_16x16x32_bf16 v[32:35], v[100:103], v[216:219], v[32:35]
	v_mfma_f32_16x16x32_bf16 v[28:31], v[124:127], v[216:219], v[28:31]
	v_mfma_f32_16x16x32_bf16 v[16:19], v[100:103], v[224:227], v[16:19]
	v_mfma_f32_16x16x32_bf16 v[12:15], v[124:127], v[224:227], v[12:15]
	v_mfma_f32_16x16x32_bf16 v[64:67], v[120:123], v[190:193], v[64:67]
	v_mfma_f32_16x16x32_bf16 v[60:63], v[144:147], v[190:193], v[60:63]
	v_mfma_f32_16x16x32_bf16 v[48:51], v[120:123], v[212:215], v[48:51]
	v_mfma_f32_16x16x32_bf16 v[44:47], v[144:147], v[212:215], v[44:47]
	v_mfma_f32_16x16x32_bf16 v[32:35], v[120:123], v[220:223], v[32:35]
	v_mfma_f32_16x16x32_bf16 v[28:31], v[144:147], v[220:223], v[28:31]
	v_mfma_f32_16x16x32_bf16 v[16:19], v[120:123], v[228:231], v[16:19]
	v_mfma_f32_16x16x32_bf16 v[12:15], v[144:147], v[228:231], v[12:15]
	s_setprio 0
	s_setprio 1
	v_mfma_f32_16x16x32_bf16 v[56:59], v[148:151], v[186:189], v[56:59]
	v_mfma_f32_16x16x32_bf16 v[52:55], v[156:159], v[186:189], v[52:55]
	v_mfma_f32_16x16x32_bf16 v[40:43], v[148:151], v[198:201], v[40:43]
	v_mfma_f32_16x16x32_bf16 v[36:39], v[156:159], v[198:201], v[36:39]
	v_mfma_f32_16x16x32_bf16 v[24:27], v[148:151], v[216:219], v[24:27]
	v_mfma_f32_16x16x32_bf16 v[20:23], v[156:159], v[216:219], v[20:23]
	v_mfma_f32_16x16x32_bf16 v[8:11], v[148:151], v[224:227], v[8:11]
	v_mfma_f32_16x16x32_bf16 v[4:7], v[156:159], v[224:227], v[4:7]
	v_mfma_f32_16x16x32_bf16 v[56:59], v[152:155], v[190:193], v[56:59]
	v_mfma_f32_16x16x32_bf16 v[52:55], v[182:185], v[190:193], v[52:55]
	v_mfma_f32_16x16x32_bf16 v[40:43], v[152:155], v[212:215], v[40:43]
	v_mfma_f32_16x16x32_bf16 v[36:39], v[182:185], v[212:215], v[36:39]
	v_mfma_f32_16x16x32_bf16 v[24:27], v[152:155], v[220:223], v[24:27]
	v_mfma_f32_16x16x32_bf16 v[20:23], v[182:185], v[220:223], v[20:23]
	v_mfma_f32_16x16x32_bf16 v[8:11], v[152:155], v[228:231], v[8:11]
	v_mfma_f32_16x16x32_bf16 v[4:7], v[182:185], v[228:231], v[4:7]
	s_setprio 0
	s_barrier
	s_add_i32 s57, s57, 2
	s_add_u32 s47, s47, 0x100
	s_addc_u32 s56, s56, 0
	s_cmp_gt_u32 s57, 61
	s_mov_b64 s[4:5], s[0:1]
	s_cbranch_scc0 .LBB0_590
	s_and_b64 vcc, exec, s[20:21]
	s_cbranch_vccz .LBB0_593
	s_barrier

; #define PG8_STAGE(bufoff, gbase, voff) do { _Pragma("unroll") for (int _i = 0; _i < 2; ++_i) \
;         __builtin_amdgcn_global_load_lds((const unsigned*)((const char*)(gbase) + (voff)[_i]), (PG8_LAS unsigned*)(lds + (bufoff) + ldsw + _i * 8192), 16, 0, 0); } while (0)
; #define PG8_LDA(dst, b, h) do { _Pragma("unroll") for (int m = 0; m < 4; ++m) _Pragma("unroll") for (int k = 0; k < 2; ++k) dst[m][k] = *(const PG8_LAS bf16x8*)(lds + PG8_SA(b, h) + aoff + m * 2048 + k * 1024); } while (0)
; #define PG8_LDB(dst, b, h) do { _Pragma("unroll") for (int n = 0; n < 2; ++n) _Pragma("unroll") for (int k = 0; k < 2; ++k) dst[n][k] = *(const PG8_LAS bf16x8*)(lds + PG8_SB(b, h) + boff + n * 2048 + k * 1024); } while (0)
; #define PG8_MMA(ai, bj, At, Bt) do { __builtin_amdgcn_s_setprio(1); _Pragma("unroll") for (int m = 0; m < 4; ++m) _Pragma("unroll") for (int n = 0; n < 2; ++n) _Pragma("unroll") for (int k = 0; k < 2; ++k) \
;         acc[ai][bj][m][n] = __builtin_amdgcn_mfma_f32_16x16x32_bf16(Bt[n][k], At[m][k], acc[ai][bj][m][n], 0, 0, 0); __builtin_amdgcn_s_setprio(0); } while (0)
; #define PG8_WAIT_V(n) asm volatile("s_waitcnt vmcnt(" #n ")" ::: "memory")
; #define PG8_WAIT_L(n) asm volatile("s_waitcnt lgkmcnt(" #n ")" ::: "memory")
; template <class Epi, class Sched, bool ALIGN_EPI = false, bool SP2 = false>
; __device__ __forceinline__ void gemm_phase(PG8_LAS unsigned char* lds, const Gemm g, const Sched& S, const Epi& E, int wave_s) {
;     ...
;             const bool last = (t == nt - 2);
;             const char* a1 = cA + (size_t)(t + 1) * kstep;
;             const char* a2 = last ? nA : cA + (size_t)(t + 2) * kstep; const char* b2 = last ? nB : cB + (size_t)(t + 2) * kstep;
;             const char* a3 = a2 + kstep; const char* b3 = b2 + kstep;
;             if (last && has_next) S.a_ready(nxt);
;             if constexpr (SP2) {
;             PG8_LDB(B0, 0, 0); PG8_LDB(B1, 0, 1); PG8_SCHED; PG8_LDA(At, 0, 0); PG8_STAGE(PG8_SA(1, 1), a1 + hstepA, voffA);
;             PG8_WAIT_V(8); PG8_WAIT_L(0); PG8_BAR; PG8_MMA(0, 0, At, B0); PG8_MMA(0, 1, At, B1); PG8_BAR; PG8_SCHED;
;             PG8_LDA(At, 0, 1); PG8_STAGE(PG8_SB(0, 0), b2, voffB); PG8_STAGE(PG8_SB(0, 1), b2 + hstepB, voffB); PG8_STAGE(PG8_SA(0, 0), a2, voffA);
;             PG8_WAIT_V(8); PG8_WAIT_L(0); PG8_BAR; PG8_MMA(1, 0, At, B0); PG8_MMA(1, 1, At, B1); PG8_BAR; PG8_SCHED;
.LBB0_661:
	s_nop 0
	s_add_u32 s26, s18, 0xfff80080
	s_addc_u32 s27, s19, -1
	s_add_i32 s74, 0, 0x10000
	s_cmp_eq_u32 s67, 28
	s_cselect_b32 s43, s7, s27
	s_cselect_b32 s42, s57, s26
	s_cselect_b32 s27, s5, s66
	s_cselect_b32 s26, s58, s59
	s_add_i32 s76, 0, 0x14000
	s_waitcnt vmcnt(0) lgkmcnt(0)
	ds_read_b128 v[108:111], v255
	ds_read_b128 v[112:115], v255 offset:1024
	ds_read_b128 v[116:119], v255 offset:2048
	ds_read_b128 v[120:123], v255 offset:3072
	ds_read_b128 v[148:151], v255 offset:16384
	ds_read_b128 v[152:155], v255 offset:17408
	ds_read_b128 v[156:159], v255 offset:18432
	ds_read_b128 v[160:163], v255 offset:19456
	s_add_i32 m0, s47, 0xc000
	ds_read_b128 v[164:167], v213
	ds_read_b128 v[190:193], v213 offset:1024
	ds_read_b128 v[194:197], v213 offset:2048
	ds_read_b128 v[198:201], v213 offset:3072
	ds_read_b128 v[214:217], v213 offset:4096
	ds_read_b128 v[218:221], v213 offset:5120
	ds_read_b128 v[222:225], v213 offset:6144
	ds_read_b128 v[226:229], v213 offset:7168
	global_load_lds_dwordx4 v188, s[18:19]
	s_add_i32 m0, s47, 0xe000
	s_nop 0
	global_load_lds_dwordx4 v186, s[18:19]
	s_waitcnt vmcnt(8)
	s_waitcnt lgkmcnt(0)
	s_barrier
	s_setprio 1
	s_waitcnt lgkmcnt(0)
	v_mfma_f32_16x16x32_bf16 v[144:147], v[108:111], v[164:167], v[144:147]
	v_mfma_f32_16x16x32_bf16 v[140:143], v[116:119], v[164:167], v[140:143]
	v_mfma_f32_16x16x32_bf16 v[136:139], v[108:111], v[194:197], v[136:139]
	v_mfma_f32_16x16x32_bf16 v[132:135], v[116:119], v[194:197], v[132:135]
	v_mfma_f32_16x16x32_bf16 v[96:99], v[108:111], v[214:217], v[96:99]
	v_mfma_f32_16x16x32_bf16 v[92:95], v[116:119], v[214:217], v[92:95]
	v_mfma_f32_16x16x32_bf16 v[80:83], v[108:111], v[222:225], v[80:83]
	v_mfma_f32_16x16x32_bf16 v[76:79], v[116:119], v[222:225], v[76:79]
	v_mfma_f32_16x16x32_bf16 v[144:147], v[112:115], v[190:193], v[144:147]
	v_mfma_f32_16x16x32_bf16 v[140:143], v[120:123], v[190:193], v[140:143]
	v_mfma_f32_16x16x32_bf16 v[136:139], v[112:115], v[198:201], v[136:139]
	v_mfma_f32_16x16x32_bf16 v[132:135], v[120:123], v[198:201], v[132:135]
	v_mfma_f32_16x16x32_bf16 v[96:99], v[112:115], v[218:221], v[96:99]
	v_mfma_f32_16x16x32_bf16 v[92:95], v[120:123], v[218:221], v[92:95]
	v_mfma_f32_16x16x32_bf16 v[80:83], v[112:115], v[226:229], v[80:83]
	v_mfma_f32_16x16x32_bf16 v[76:79], v[120:123], v[226:229], v[76:79]
	s_setprio 0
	s_setprio 1
	v_mfma_f32_16x16x32_bf16 v[128:131], v[148:151], v[164:167], v[128:131]
	v_mfma_f32_16x16x32_bf16 v[124:127], v[156:159], v[164:167], v[124:127]
	v_mfma_f32_16x16x32_bf16 v[104:107], v[148:151], v[194:197], v[104:107]
	v_mfma_f32_16x16x32_bf16 v[100:103], v[156:159], v[194:197], v[100:103]
	v_mfma_f32_16x16x32_bf16 v[88:91], v[148:151], v[214:217], v[88:91]
	v_mfma_f32_16x16x32_bf16 v[84:87], v[156:159], v[214:217], v[84:87]
	v_mfma_f32_16x16x32_bf16 v[72:75], v[148:151], v[222:225], v[72:75]
	v_mfma_f32_16x16x32_bf16 v[68:71], v[156:159], v[222:225], v[68:71]
	v_mfma_f32_16x16x32_bf16 v[128:131], v[152:155], v[190:193], v[128:131]
	v_mfma_f32_16x16x32_bf16 v[124:127], v[160:163], v[190:193], v[124:127]
	v_mfma_f32_16x16x32_bf16 v[104:107], v[152:155], v[198:201], v[104:107]
	v_mfma_f32_16x16x32_bf16 v[100:103], v[160:163], v[198:201], v[100:103]
	v_mfma_f32_16x16x32_bf16 v[88:91], v[152:155], v[218:221], v[88:91]
	v_mfma_f32_16x16x32_bf16 v[84:87], v[160:163], v[218:221], v[84:87]
	v_mfma_f32_16x16x32_bf16 v[72:75], v[152:155], v[226:229], v[72:75]
	v_mfma_f32_16x16x32_bf16 v[68:71], v[160:163], v[226:229], v[68:71]
	s_setprio 0
	s_barrier
	s_add_i32 s74, s74, s46
	s_add_u32 s98, s26, s60
	s_addc_u32 s99, s27, s61
	s_mov_b32 m0, s74
	ds_read_b128 v[164:167], v213 offset:16384
	ds_read_b128 v[190:193], v213 offset:17408
	ds_read_b128 v[194:197], v213 offset:18432
	ds_read_b128 v[198:201], v213 offset:19456
	ds_read_b128 v[214:217], v213 offset:20480
	ds_read_b128 v[218:221], v213 offset:21504
	ds_read_b128 v[222:225], v213 offset:22528
	ds_read_b128 v[226:229], v213 offset:23552
	global_load_lds_dwordx4 v2, s[26:27]
	s_add_i32 m0, s74, 0x2000
	s_add_u32 s74, s26, 0x80000
	s_addc_u32 s75, s27, 0
	s_add_i32 s76, s76, s46
	global_load_lds_dwordx4 v0, s[26:27]
	s_mov_b32 m0, s76
	s_add_u32 s100, s42, s60
	s_addc_u32 s101, s43, s61
	s_nop 0
	global_load_lds_dwordx4 v2, s[74:75]
	s_add_i32 m0, s76, 0x2000
	s_nop 0
	global_load_lds_dwordx4 v0, s[74:75]
	s_mov_b32 m0, s47
	s_nop 0
	global_load_lds_dwordx4 v184, s[42:43]
	s_mov_b32 m0, s48
	s_nop 0
	global_load_lds_dwordx4 v182, s[42:43]
	s_waitcnt vmcnt(8)
	s_waitcnt lgkmcnt(0)
	s_barrier
; #define PG8_STAGE(bufoff, gbase, voff) do { _Pragma("unroll") for (int _i = 0; _i < 2; ++_i) \
;         __builtin_amdgcn_global_load_lds((const unsigned*)((const char*)(gbase) + (voff)[_i]), (PG8_LAS unsigned*)(lds + (bufoff) + ldsw + _i * 8192), 16, 0, 0); } while (0)
; #define PG8_LDA(dst, b, h) do { _Pragma("unroll") for (int m = 0; m < 4; ++m) _Pragma("unroll") for (int k = 0; k < 2; ++k) dst[m][k] = *(const PG8_LAS bf16x8*)(lds + PG8_SA(b, h) + aoff + m * 2048 + k * 1024); } while (0)
; #define PG8_LDB(dst, b, h) do { _Pragma("unroll") for (int n = 0; n < 2; ++n) _Pragma("unroll") for (int k = 0; k < 2; ++k) dst[n][k] = *(const PG8_LAS bf16x8*)(lds + PG8_SB(b, h) + boff + n * 2048 + k * 1024); } while (0)
; #define PG8_MMA(ai, bj, At, Bt) do { __builtin_amdgcn_s_setprio(1); _Pragma("unroll") for (int m = 0; m < 4; ++m) _Pragma("unroll") for (int n = 0; n < 2; ++n) _Pragma("unroll") for (int k = 0; k < 2; ++k) \
;         acc[ai][bj][m][n] = __builtin_amdgcn_mfma_f32_16x16x32_bf16(Bt[n][k], At[m][k], acc[ai][bj][m][n], 0, 0, 0); __builtin_amdgcn_s_setprio(0); } while (0)
; #define PG8_WAIT_V(n) asm volatile("s_waitcnt vmcnt(" #n ")" ::: "memory")
; #define PG8_WAIT_L(n) asm volatile("s_waitcnt lgkmcnt(" #n ")" ::: "memory")
; #define PG8_BAR __builtin_amdgcn_s_barrier()
; #define PG8_SCHED __builtin_amdgcn_sched_barrier(0)
; template <class Epi, class Sched, bool ALIGN_EPI = false, bool SP2 = false>
; __device__ __forceinline__ void gemm_phase(PG8_LAS unsigned char* lds, const Gemm g, const Sched& S, const Epi& E, int wave_s) {
;     ...
;             PG8_WAIT_V(8); PG8_WAIT_L(0); PG8_BAR; PG8_MMA(1, 0, At, B0); PG8_MMA(1, 1, At, B1); PG8_BAR; PG8_SCHED;
;             PG8_LDB(B0, 1, 0); PG8_LDB(B1, 1, 1); PG8_SCHED; PG8_LDA(At, 1, 0); PG8_STAGE(PG8_SA(0, 1), a2 + hstepA, voffA);
;             PG8_WAIT_V(8); PG8_WAIT_L(0); PG8_BAR; PG8_MMA(0, 0, At, B0); PG8_MMA(0, 1, At, B1); PG8_BAR; PG8_SCHED;
	s_setprio 1
	s_waitcnt lgkmcnt(0)
	v_mfma_f32_16x16x32_bf16 v[64:67], v[108:111], v[164:167], v[64:67]
	v_mfma_f32_16x16x32_bf16 v[60:63], v[116:119], v[164:167], v[60:63]
	v_mfma_f32_16x16x32_bf16 v[48:51], v[108:111], v[194:197], v[48:51]
	v_mfma_f32_16x16x32_bf16 v[44:47], v[116:119], v[194:197], v[44:47]
	v_mfma_f32_16x16x32_bf16 v[32:35], v[108:111], v[214:217], v[32:35]
	v_mfma_f32_16x16x32_bf16 v[28:31], v[116:119], v[214:217], v[28:31]
	v_mfma_f32_16x16x32_bf16 v[16:19], v[108:111], v[222:225], v[16:19]
	v_mfma_f32_16x16x32_bf16 v[12:15], v[116:119], v[222:225], v[12:15]
	v_mfma_f32_16x16x32_bf16 v[64:67], v[112:115], v[190:193], v[64:67]
	v_mfma_f32_16x16x32_bf16 v[60:63], v[120:123], v[190:193], v[60:63]
	v_mfma_f32_16x16x32_bf16 v[48:51], v[112:115], v[198:201], v[48:51]
	v_mfma_f32_16x16x32_bf16 v[44:47], v[120:123], v[198:201], v[44:47]
	v_mfma_f32_16x16x32_bf16 v[32:35], v[112:115], v[218:221], v[32:35]
	v_mfma_f32_16x16x32_bf16 v[28:31], v[120:123], v[218:221], v[28:31]
	v_mfma_f32_16x16x32_bf16 v[16:19], v[112:115], v[226:229], v[16:19]
	v_mfma_f32_16x16x32_bf16 v[12:15], v[120:123], v[226:229], v[12:15]
	s_setprio 0
	s_setprio 1
	v_mfma_f32_16x16x32_bf16 v[56:59], v[148:151], v[164:167], v[56:59]
	v_mfma_f32_16x16x32_bf16 v[52:55], v[156:159], v[164:167], v[52:55]
	v_mfma_f32_16x16x32_bf16 v[40:43], v[148:151], v[194:197], v[40:43]
	v_mfma_f32_16x16x32_bf16 v[36:39], v[156:159], v[194:197], v[36:39]
	v_mfma_f32_16x16x32_bf16 v[24:27], v[148:151], v[214:217], v[24:27]
	v_mfma_f32_16x16x32_bf16 v[20:23], v[156:159], v[214:217], v[20:23]
	v_mfma_f32_16x16x32_bf16 v[8:11], v[148:151], v[222:225], v[8:11]
	v_mfma_f32_16x16x32_bf16 v[4:7], v[156:159], v[222:225], v[4:7]
	v_mfma_f32_16x16x32_bf16 v[56:59], v[152:155], v[190:193], v[56:59]
	v_mfma_f32_16x16x32_bf16 v[52:55], v[160:163], v[190:193], v[52:55]
	v_mfma_f32_16x16x32_bf16 v[40:43], v[152:155], v[198:201], v[40:43]
	v_mfma_f32_16x16x32_bf16 v[36:39], v[160:163], v[198:201], v[36:39]
	v_mfma_f32_16x16x32_bf16 v[24:27], v[152:155], v[218:221], v[24:27]
	v_mfma_f32_16x16x32_bf16 v[20:23], v[160:163], v[218:221], v[20:23]
	v_mfma_f32_16x16x32_bf16 v[8:11], v[152:155], v[226:229], v[8:11]
	v_mfma_f32_16x16x32_bf16 v[4:7], v[160:163], v[226:229], v[4:7]
	s_setprio 0
	s_barrier
	s_nop 0
	s_add_i32 s74, 0, 0x18000
	s_add_i32 s75, 0, 0x1c000
	ds_read_b128 v[108:111], v255 offset:32768
	ds_read_b128 v[112:115], v255 offset:33792
	ds_read_b128 v[116:119], v255 offset:34816
	ds_read_b128 v[120:123], v255 offset:35840
	ds_read_b128 v[148:151], v255 offset:49152
	ds_read_b128 v[152:155], v255 offset:50176
	ds_read_b128 v[156:159], v255 offset:51200
	ds_read_b128 v[160:163], v255 offset:52224
	s_add_u32 s42, s42, 0x80000
	s_addc_u32 s43, s43, 0
	s_mov_b32 m0, s49
	ds_read_b128 v[164:167], v213 offset:32768
	ds_read_b128 v[190:193], v213 offset:33792
	ds_read_b128 v[194:197], v213 offset:34816
	ds_read_b128 v[198:201], v213 offset:35840
	ds_read_b128 v[214:217], v213 offset:36864
	ds_read_b128 v[218:221], v213 offset:37888
	ds_read_b128 v[222:225], v213 offset:38912
	ds_read_b128 v[226:229], v213 offset:39936
	global_load_lds_dwordx4 v184, s[42:43]
	s_mov_b32 m0, s50
	s_nop 0
	global_load_lds_dwordx4 v182, s[42:43]
	s_waitcnt vmcnt(8)
	s_waitcnt lgkmcnt(0)
	s_barrier
	s_setprio 1
	s_waitcnt lgkmcnt(0)
	v_mfma_f32_16x16x32_bf16 v[144:147], v[108:111], v[164:167], v[144:147]
	v_mfma_f32_16x16x32_bf16 v[140:143], v[116:119], v[164:167], v[140:143]
	v_mfma_f32_16x16x32_bf16 v[136:139], v[108:111], v[194:197], v[136:139]
	v_mfma_f32_16x16x32_bf16 v[132:135], v[116:119], v[194:197], v[132:135]
	v_mfma_f32_16x16x32_bf16 v[96:99], v[108:111], v[214:217], v[96:99]
	v_mfma_f32_16x16x32_bf16 v[92:95], v[116:119], v[214:217], v[92:95]
	v_mfma_f32_16x16x32_bf16 v[80:83], v[108:111], v[222:225], v[80:83]
	v_mfma_f32_16x16x32_bf16 v[76:79], v[116:119], v[222:225], v[76:79]
	v_mfma_f32_16x16x32_bf16 v[144:147], v[112:115], v[190:193], v[144:147]
	v_mfma_f32_16x16x32_bf16 v[140:143], v[120:123], v[190:193], v[140:143]
	v_mfma_f32_16x16x32_bf16 v[136:139], v[112:115], v[198:201], v[136:139]
	v_mfma_f32_16x16x32_bf16 v[132:135], v[120:123], v[198:201], v[132:135]
	v_mfma_f32_16x16x32_bf16 v[96:99], v[112:115], v[218:221], v[96:99]
	v_mfma_f32_16x16x32_bf16 v[92:95], v[120:123], v[218:221], v[92:95]
	v_mfma_f32_16x16x32_bf16 v[80:83], v[112:115], v[226:229], v[80:83]
	v_mfma_f32_16x16x32_bf16 v[76:79], v[120:123], v[226:229], v[76:79]
	s_setprio 0
	s_setprio 1
	v_mfma_f32_16x16x32_bf16 v[128:131], v[148:151], v[164:167], v[128:131]
	v_mfma_f32_16x16x32_bf16 v[124:127], v[156:159], v[164:167], v[124:127]
	v_mfma_f32_16x16x32_bf16 v[104:107], v[148:151], v[194:197], v[104:107]
	v_mfma_f32_16x16x32_bf16 v[100:103], v[156:159], v[194:197], v[100:103]
	v_mfma_f32_16x16x32_bf16 v[88:91], v[148:151], v[214:217], v[88:91]
	v_mfma_f32_16x16x32_bf16 v[84:87], v[156:159], v[214:217], v[84:87]
	v_mfma_f32_16x16x32_bf16 v[72:75], v[148:151], v[222:225], v[72:75]
	v_mfma_f32_16x16x32_bf16 v[68:71], v[156:159], v[222:225], v[68:71]
	v_mfma_f32_16x16x32_bf16 v[128:131], v[152:155], v[190:193], v[128:131]
	v_mfma_f32_16x16x32_bf16 v[124:127], v[160:163], v[190:193], v[124:127]
	v_mfma_f32_16x16x32_bf16 v[104:107], v[152:155], v[198:201], v[104:107]
	v_mfma_f32_16x16x32_bf16 v[100:103], v[160:163], v[198:201], v[100:103]
	v_mfma_f32_16x16x32_bf16 v[88:91], v[152:155], v[218:221], v[88:91]
	v_mfma_f32_16x16x32_bf16 v[84:87], v[160:163], v[218:221], v[84:87]
	v_mfma_f32_16x16x32_bf16 v[72:75], v[152:155], v[226:229], v[72:75]
	v_mfma_f32_16x16x32_bf16 v[68:71], v[160:163], v[226:229], v[68:71]
	s_setprio 0
	s_barrier
; #define PG8_STAGE(bufoff, gbase, voff) do { _Pragma("unroll") for (int _i = 0; _i < 2; ++_i) \
;         __builtin_amdgcn_global_load_lds((const unsigned*)((const char*)(gbase) + (voff)[_i]), (PG8_LAS unsigned*)(lds + (bufoff) + ldsw + _i * 8192), 16, 0, 0); } while (0)
; #define PG8_LDA(dst, b, h) do { _Pragma("unroll") for (int m = 0; m < 4; ++m) _Pragma("unroll") for (int k = 0; k < 2; ++k) dst[m][k] = *(const PG8_LAS bf16x8*)(lds + PG8_SA(b, h) + aoff + m * 2048 + k * 1024); } while (0)
; #define PG8_MMA(ai, bj, At, Bt) do { __builtin_amdgcn_s_setprio(1); _Pragma("unroll") for (int m = 0; m < 4; ++m) _Pragma("unroll") for (int n = 0; n < 2; ++n) _Pragma("unroll") for (int k = 0; k < 2; ++k) \
;         acc[ai][bj][m][n] = __builtin_amdgcn_mfma_f32_16x16x32_bf16(Bt[n][k], At[m][k], acc[ai][bj][m][n], 0, 0, 0); __builtin_amdgcn_s_setprio(0); } while (0)
; #define PG8_WAIT_V(n) asm volatile("s_waitcnt vmcnt(" #n ")" ::: "memory")
; #define PG8_WAIT_L(n) asm volatile("s_waitcnt lgkmcnt(" #n ")" ::: "memory")
; #define PG8_BAR __builtin_amdgcn_s_barrier()
; #define PG8_SCHED __builtin_amdgcn_sched_barrier(0)
; template <class Epi, class Sched, bool ALIGN_EPI = false, bool SP2 = false>
; __device__ __forceinline__ void gemm_phase(PG8_LAS unsigned char* lds, const Gemm g, const Sched& S, const Epi& E, int wave_s) {
;     ...
;             PG8_LDA(At, 1, 1); PG8_STAGE(PG8_SB(1, 0), b3, voffB); PG8_STAGE(PG8_SB(1, 1), b3 + hstepB, voffB); PG8_STAGE(PG8_SA(1, 0), a3, voffA);
;             PG8_WAIT_V(8); PG8_WAIT_L(0); PG8_BAR; PG8_MMA(1, 0, At, B0); PG8_MMA(1, 1, At, B1); PG8_BAR; PG8_SCHED;
	s_add_i32 s42, s74, s46
	s_mov_b32 m0, s42
	ds_read_b128 v[164:167], v213 offset:49152
	ds_read_b128 v[190:193], v213 offset:50176
	ds_read_b128 v[194:197], v213 offset:51200
	ds_read_b128 v[198:201], v213 offset:52224
	ds_read_b128 v[214:217], v213 offset:53248
	ds_read_b128 v[218:221], v213 offset:54272
	ds_read_b128 v[222:225], v213 offset:55296
	ds_read_b128 v[226:229], v213 offset:56320
	global_load_lds_dwordx4 v2, s[98:99]
	s_add_i32 m0, s42, 0x2000
	s_add_u32 s26, s26, 0x80080
	s_addc_u32 s27, s27, 0
	s_add_i32 s42, s75, s46
	global_load_lds_dwordx4 v0, s[98:99]
	s_mov_b32 m0, s42
	s_nop 0
	global_load_lds_dwordx4 v2, s[26:27]
	s_add_i32 m0, s42, 0x2000
	s_nop 0
	global_load_lds_dwordx4 v0, s[26:27]
	s_mov_b32 m0, s54
	s_nop 0
	global_load_lds_dwordx4 v184, s[100:101]
	s_mov_b32 m0, s55
	s_nop 0
	global_load_lds_dwordx4 v182, s[100:101]
	s_waitcnt vmcnt(8)
	s_waitcnt lgkmcnt(0)
	s_barrier
	s_setprio 1
	s_waitcnt lgkmcnt(0)
	v_mfma_f32_16x16x32_bf16 v[64:67], v[108:111], v[164:167], v[64:67]
	v_mfma_f32_16x16x32_bf16 v[60:63], v[116:119], v[164:167], v[60:63]
	v_mfma_f32_16x16x32_bf16 v[48:51], v[108:111], v[194:197], v[48:51]
	v_mfma_f32_16x16x32_bf16 v[44:47], v[116:119], v[194:197], v[44:47]
	v_mfma_f32_16x16x32_bf16 v[32:35], v[108:111], v[214:217], v[32:35]
	v_mfma_f32_16x16x32_bf16 v[28:31], v[116:119], v[214:217], v[28:31]
	v_mfma_f32_16x16x32_bf16 v[16:19], v[108:111], v[222:225], v[16:19]
	v_mfma_f32_16x16x32_bf16 v[12:15], v[116:119], v[222:225], v[12:15]
	v_mfma_f32_16x16x32_bf16 v[64:67], v[112:115], v[190:193], v[64:67]
	v_mfma_f32_16x16x32_bf16 v[60:63], v[120:123], v[190:193], v[60:63]
	v_mfma_f32_16x16x32_bf16 v[48:51], v[112:115], v[198:201], v[48:51]
	v_mfma_f32_16x16x32_bf16 v[44:47], v[120:123], v[198:201], v[44:47]
	v_mfma_f32_16x16x32_bf16 v[32:35], v[112:115], v[218:221], v[32:35]
	v_mfma_f32_16x16x32_bf16 v[28:31], v[120:123], v[218:221], v[28:31]
	v_mfma_f32_16x16x32_bf16 v[16:19], v[112:115], v[226:229], v[16:19]
	v_mfma_f32_16x16x32_bf16 v[12:15], v[120:123], v[226:229], v[12:15]
	s_setprio 0
	s_setprio 1
	v_mfma_f32_16x16x32_bf16 v[56:59], v[148:151], v[164:167], v[56:59]
	v_mfma_f32_16x16x32_bf16 v[52:55], v[156:159], v[164:167], v[52:55]
	v_mfma_f32_16x16x32_bf16 v[40:43], v[148:151], v[194:197], v[40:43]
	v_mfma_f32_16x16x32_bf16 v[36:39], v[156:159], v[194:197], v[36:39]
	v_mfma_f32_16x16x32_bf16 v[24:27], v[148:151], v[214:217], v[24:27]
	v_mfma_f32_16x16x32_bf16 v[20:23], v[156:159], v[214:217], v[20:23]
	v_mfma_f32_16x16x32_bf16 v[8:11], v[148:151], v[222:225], v[8:11]
	v_mfma_f32_16x16x32_bf16 v[4:7], v[156:159], v[222:225], v[4:7]
	v_mfma_f32_16x16x32_bf16 v[56:59], v[152:155], v[190:193], v[56:59]
	v_mfma_f32_16x16x32_bf16 v[52:55], v[160:163], v[190:193], v[52:55]
	v_mfma_f32_16x16x32_bf16 v[40:43], v[152:155], v[198:201], v[40:43]
	v_mfma_f32_16x16x32_bf16 v[36:39], v[160:163], v[198:201], v[36:39]
	v_mfma_f32_16x16x32_bf16 v[24:27], v[152:155], v[218:221], v[24:27]
	v_mfma_f32_16x16x32_bf16 v[20:23], v[160:163], v[218:221], v[20:23]
	v_mfma_f32_16x16x32_bf16 v[8:11], v[152:155], v[226:229], v[8:11]
	v_mfma_f32_16x16x32_bf16 v[4:7], v[160:163], v[226:229], v[4:7]
	s_setprio 0
	s_barrier
	s_add_i32 s67, s67, 2
	s_add_u32 s59, s59, 0x100
	s_addc_u32 s66, s66, 0
	s_add_u32 s18, s18, 0x100
	s_addc_u32 s19, s19, 0
	s_cmp_gt_u32 s67, 29
	s_cbranch_scc0 .LBB0_661
	s_and_b64 vcc, exec, s[38:39]
	s_cbranch_vccz .LBB0_664
	s_barrier

; #define PG8_STAGE(bufoff, gbase, voff) do { _Pragma("unroll") for (int _i = 0; _i < 2; ++_i) \
;         __builtin_amdgcn_global_load_lds((const unsigned*)((const char*)(gbase) + (voff)[_i]), (PG8_LAS unsigned*)(lds + (bufoff) + ldsw + _i * 8192), 16, 0, 0); } while (0)
; #define PG8_LDA(dst, b, h) do { _Pragma("unroll") for (int m = 0; m < 4; ++m) _Pragma("unroll") for (int k = 0; k < 2; ++k) dst[m][k] = *(const PG8_LAS bf16x8*)(lds + PG8_SA(b, h) + aoff + m * 2048 + k * 1024); } while (0)
; #define PG8_LDB(dst, b, h) do { _Pragma("unroll") for (int n = 0; n < 2; ++n) _Pragma("unroll") for (int k = 0; k < 2; ++k) dst[n][k] = *(const PG8_LAS bf16x8*)(lds + PG8_SB(b, h) + boff + n * 2048 + k * 1024); } while (0)
; #define PG8_MMA(ai, bj, At, Bt) do { __builtin_amdgcn_s_setprio(1); _Pragma("unroll") for (int m = 0; m < 4; ++m) _Pragma("unroll") for (int n = 0; n < 2; ++n) _Pragma("unroll") for (int k = 0; k < 2; ++k) \
;         acc[ai][bj][m][n] = __builtin_amdgcn_mfma_f32_16x16x32_bf16(Bt[n][k], At[m][k], acc[ai][bj][m][n], 0, 0, 0); __builtin_amdgcn_s_setprio(0); } while (0)
; #define PG8_WAIT_V(n) asm volatile("s_waitcnt vmcnt(" #n ")" ::: "memory")
; #define PG8_WAIT_L(n) asm volatile("s_waitcnt lgkmcnt(" #n ")" ::: "memory")
; template <class Epi, class Sched, bool ALIGN_EPI = false, bool SP2 = false>
; __device__ __forceinline__ void gemm_phase(PG8_LAS unsigned char* lds, const Gemm g, const Sched& S, const Epi& E, int wave_s) {
;     ...
;             const bool last = (t == nt - 2);
;             const char* a1 = cA + (size_t)(t + 1) * kstep;
;             const char* a2 = last ? nA : cA + (size_t)(t + 2) * kstep; const char* b2 = last ? nB : cB + (size_t)(t + 2) * kstep;
;             const char* a3 = a2 + kstep; const char* b3 = b2 + kstep;
;             if (last && has_next) S.a_ready(nxt);
;             if constexpr (SP2) {
;             PG8_LDB(B0, 0, 0); PG8_LDB(B1, 0, 1); PG8_SCHED; PG8_LDA(At, 0, 0); PG8_STAGE(PG8_SA(1, 1), a1 + hstepA, voffA);
;             PG8_WAIT_V(8); PG8_WAIT_L(0); PG8_BAR; PG8_MMA(0, 0, At, B0); PG8_MMA(0, 1, At, B1); PG8_BAR; PG8_SCHED;
;             PG8_LDA(At, 0, 1); PG8_STAGE(PG8_SB(0, 0), b2, voffB); PG8_STAGE(PG8_SB(0, 1), b2 + hstepB, voffB); PG8_STAGE(PG8_SA(0, 0), a2, voffA);
;             PG8_WAIT_V(8); PG8_WAIT_L(0); PG8_BAR; PG8_MMA(1, 0, At, B0); PG8_MMA(1, 1, At, B1); PG8_BAR; PG8_SCHED;
.LBB0_790:
	s_add_u32 s26, s18, 0xfff80080
	s_addc_u32 s27, s19, -1
	s_add_i32 s56, 0, 0x10000
	s_cmp_eq_u32 s55, 28
	s_cselect_b32 s39, s21, s27
	s_cselect_b32 s38, s51, s26
	s_cselect_b32 s27, s17, s54
	s_cselect_b32 s26, s52, s53
	s_add_i32 s58, 0, 0x14000
	ds_read_b128 v[146:149], v255
	ds_read_b128 v[150:153], v255 offset:1024
	ds_read_b128 v[154:157], v255 offset:2048
	ds_read_b128 v[158:161], v255 offset:3072
	ds_read_b128 v[162:165], v255 offset:16384
	ds_read_b128 v[182:185], v255 offset:17408
	ds_read_b128 v[186:189], v255 offset:18432
	ds_read_b128 v[190:193], v255 offset:19456
	s_add_i32 m0, s43, 0xc000
	ds_read_b128 v[194:197], v145
	ds_read_b128 v[198:201], v145 offset:1024
	ds_read_b128 v[212:215], v145 offset:2048
	ds_read_b128 v[216:219], v145 offset:3072
	ds_read_b128 v[220:223], v145 offset:4096
	ds_read_b128 v[224:227], v145 offset:5120
	ds_read_b128 v[228:231], v145 offset:6144
	ds_read_b128 v[232:235], v145 offset:7168
	global_load_lds_dwordx4 v138, s[18:19]
	s_add_i32 m0, s43, 0xe000
	s_nop 0
	global_load_lds_dwordx4 v136, s[18:19]
	s_waitcnt vmcnt(8)
	s_waitcnt lgkmcnt(0)
	s_barrier
	s_setprio 1
	s_waitcnt lgkmcnt(0)
	v_mfma_f32_16x16x32_bf16 v[128:131], v[146:149], v[194:197], v[128:131]
	v_mfma_f32_16x16x32_bf16 v[120:123], v[154:157], v[194:197], v[120:123]
	v_mfma_f32_16x16x32_bf16 v[112:115], v[146:149], v[212:215], v[112:115]
	v_mfma_f32_16x16x32_bf16 v[104:107], v[154:157], v[212:215], v[104:107]
	v_mfma_f32_16x16x32_bf16 v[96:99], v[146:149], v[220:223], v[96:99]
	v_mfma_f32_16x16x32_bf16 v[88:91], v[154:157], v[220:223], v[88:91]
	v_mfma_f32_16x16x32_bf16 v[80:83], v[146:149], v[228:231], v[80:83]
	v_mfma_f32_16x16x32_bf16 v[72:75], v[154:157], v[228:231], v[72:75]
	v_mfma_f32_16x16x32_bf16 v[128:131], v[150:153], v[198:201], v[128:131]
	v_mfma_f32_16x16x32_bf16 v[120:123], v[158:161], v[198:201], v[120:123]
	v_mfma_f32_16x16x32_bf16 v[112:115], v[150:153], v[216:219], v[112:115]
	v_mfma_f32_16x16x32_bf16 v[104:107], v[158:161], v[216:219], v[104:107]
	v_mfma_f32_16x16x32_bf16 v[96:99], v[150:153], v[224:227], v[96:99]
	v_mfma_f32_16x16x32_bf16 v[88:91], v[158:161], v[224:227], v[88:91]
	v_mfma_f32_16x16x32_bf16 v[80:83], v[150:153], v[232:235], v[80:83]
	v_mfma_f32_16x16x32_bf16 v[72:75], v[158:161], v[232:235], v[72:75]
	s_setprio 0
	s_setprio 1
	v_mfma_f32_16x16x32_bf16 v[124:127], v[162:165], v[194:197], v[124:127]
	v_mfma_f32_16x16x32_bf16 v[116:119], v[186:189], v[194:197], v[116:119]
	v_mfma_f32_16x16x32_bf16 v[108:111], v[162:165], v[212:215], v[108:111]
	v_mfma_f32_16x16x32_bf16 v[100:103], v[186:189], v[212:215], v[100:103]
	v_mfma_f32_16x16x32_bf16 v[92:95], v[162:165], v[220:223], v[92:95]
	v_mfma_f32_16x16x32_bf16 v[84:87], v[186:189], v[220:223], v[84:87]
	v_mfma_f32_16x16x32_bf16 v[76:79], v[162:165], v[228:231], v[76:79]
	v_mfma_f32_16x16x32_bf16 v[68:71], v[186:189], v[228:231], v[68:71]
	v_mfma_f32_16x16x32_bf16 v[124:127], v[182:185], v[198:201], v[124:127]
	v_mfma_f32_16x16x32_bf16 v[116:119], v[190:193], v[198:201], v[116:119]
	v_mfma_f32_16x16x32_bf16 v[108:111], v[182:185], v[216:219], v[108:111]
	v_mfma_f32_16x16x32_bf16 v[100:103], v[190:193], v[216:219], v[100:103]
	v_mfma_f32_16x16x32_bf16 v[92:95], v[182:185], v[224:227], v[92:95]
	v_mfma_f32_16x16x32_bf16 v[84:87], v[190:193], v[224:227], v[84:87]
	v_mfma_f32_16x16x32_bf16 v[76:79], v[182:185], v[232:235], v[76:79]
	v_mfma_f32_16x16x32_bf16 v[68:71], v[190:193], v[232:235], v[68:71]
	s_setprio 0
	s_barrier
	s_add_i32 s56, s56, s42
	s_add_u32 s98, s26, s60
	s_addc_u32 s99, s27, s61
	s_mov_b32 m0, s56
	ds_read_b128 v[194:197], v145 offset:16384
	ds_read_b128 v[198:201], v145 offset:17408
	ds_read_b128 v[212:215], v145 offset:18432
	ds_read_b128 v[216:219], v145 offset:19456
	ds_read_b128 v[220:223], v145 offset:20480
	ds_read_b128 v[224:227], v145 offset:21504
	ds_read_b128 v[228:231], v145 offset:22528
	ds_read_b128 v[232:235], v145 offset:23552
	global_load_lds_dwordx4 v2, s[26:27]
	s_add_i32 m0, s56, 0x2000
	s_add_u32 s56, s26, 0x80000
	s_addc_u32 s57, s27, 0
	s_add_i32 s58, s58, s42
	global_load_lds_dwordx4 v0, s[26:27]
	s_mov_b32 m0, s58
	s_add_u32 s100, s38, s60
	s_addc_u32 s101, s39, s61
	s_nop 0
	global_load_lds_dwordx4 v2, s[56:57]
	s_add_i32 m0, s58, 0x2000
	s_nop 0
	global_load_lds_dwordx4 v0, s[56:57]
	s_mov_b32 m0, s43
	s_nop 0
	global_load_lds_dwordx4 v134, s[38:39]
	s_mov_b32 m0, s44
	s_nop 0
	global_load_lds_dwordx4 v132, s[38:39]
	s_waitcnt vmcnt(8)
	s_waitcnt lgkmcnt(0)
	s_barrier
	s_setprio 1
	s_waitcnt lgkmcnt(0)
	v_mfma_f32_16x16x32_bf16 v[64:67], v[146:149], v[194:197], v[64:67]
	v_mfma_f32_16x16x32_bf16 v[56:59], v[154:157], v[194:197], v[56:59]
	v_mfma_f32_16x16x32_bf16 v[48:51], v[146:149], v[212:215], v[48:51]
	v_mfma_f32_16x16x32_bf16 v[40:43], v[154:157], v[212:215], v[40:43]
	v_mfma_f32_16x16x32_bf16 v[32:35], v[146:149], v[220:223], v[32:35]
	v_mfma_f32_16x16x32_bf16 v[24:27], v[154:157], v[220:223], v[24:27]
	v_mfma_f32_16x16x32_bf16 v[16:19], v[146:149], v[228:231], v[16:19]
	v_mfma_f32_16x16x32_bf16 v[8:11], v[154:157], v[228:231], v[8:11]
	v_mfma_f32_16x16x32_bf16 v[64:67], v[150:153], v[198:201], v[64:67]
	v_mfma_f32_16x16x32_bf16 v[56:59], v[158:161], v[198:201], v[56:59]
	v_mfma_f32_16x16x32_bf16 v[48:51], v[150:153], v[216:219], v[48:51]
	v_mfma_f32_16x16x32_bf16 v[40:43], v[158:161], v[216:219], v[40:43]
	v_mfma_f32_16x16x32_bf16 v[32:35], v[150:153], v[224:227], v[32:35]
	v_mfma_f32_16x16x32_bf16 v[24:27], v[158:161], v[224:227], v[24:27]
	v_mfma_f32_16x16x32_bf16 v[16:19], v[150:153], v[232:235], v[16:19]
	v_mfma_f32_16x16x32_bf16 v[8:11], v[158:161], v[232:235], v[8:11]
	s_setprio 0
	s_setprio 1
	v_mfma_f32_16x16x32_bf16 v[60:63], v[162:165], v[194:197], v[60:63]
	v_mfma_f32_16x16x32_bf16 v[52:55], v[186:189], v[194:197], v[52:55]
	v_mfma_f32_16x16x32_bf16 v[44:47], v[162:165], v[212:215], v[44:47]
	v_mfma_f32_16x16x32_bf16 v[36:39], v[186:189], v[212:215], v[36:39]
	v_mfma_f32_16x16x32_bf16 v[28:31], v[162:165], v[220:223], v[28:31]
	v_mfma_f32_16x16x32_bf16 v[20:23], v[186:189], v[220:223], v[20:23]
	v_mfma_f32_16x16x32_bf16 v[12:15], v[162:165], v[228:231], v[12:15]
	v_mfma_f32_16x16x32_bf16 v[4:7], v[186:189], v[228:231], v[4:7]
	v_mfma_f32_16x16x32_bf16 v[60:63], v[182:185], v[198:201], v[60:63]
	v_mfma_f32_16x16x32_bf16 v[52:55], v[190:193], v[198:201], v[52:55]
	v_mfma_f32_16x16x32_bf16 v[44:47], v[182:185], v[216:219], v[44:47]
	v_mfma_f32_16x16x32_bf16 v[36:39], v[190:193], v[216:219], v[36:39]
	v_mfma_f32_16x16x32_bf16 v[28:31], v[182:185], v[224:227], v[28:31]
	v_mfma_f32_16x16x32_bf16 v[20:23], v[190:193], v[224:227], v[20:23]
	v_mfma_f32_16x16x32_bf16 v[12:15], v[182:185], v[232:235], v[12:15]
	v_mfma_f32_16x16x32_bf16 v[4:7], v[190:193], v[232:235], v[4:7]
	s_setprio 0
	s_barrier
; #define PG8_STAGE(bufoff, gbase, voff) do { _Pragma("unroll") for (int _i = 0; _i < 2; ++_i) \
;         __builtin_amdgcn_global_load_lds((const unsigned*)((const char*)(gbase) + (voff)[_i]), (PG8_LAS unsigned*)(lds + (bufoff) + ldsw + _i * 8192), 16, 0, 0); } while (0)
; #define PG8_LDA(dst, b, h) do { _Pragma("unroll") for (int m = 0; m < 4; ++m) _Pragma("unroll") for (int k = 0; k < 2; ++k) dst[m][k] = *(const PG8_LAS bf16x8*)(lds + PG8_SA(b, h) + aoff + m * 2048 + k * 1024); } while (0)
; #define PG8_LDB(dst, b, h) do { _Pragma("unroll") for (int n = 0; n < 2; ++n) _Pragma("unroll") for (int k = 0; k < 2; ++k) dst[n][k] = *(const PG8_LAS bf16x8*)(lds + PG8_SB(b, h) + boff + n * 2048 + k * 1024); } while (0)
; #define PG8_MMA(ai, bj, At, Bt) do { __builtin_amdgcn_s_setprio(1); _Pragma("unroll") for (int m = 0; m < 4; ++m) _Pragma("unroll") for (int n = 0; n < 2; ++n) _Pragma("unroll") for (int k = 0; k < 2; ++k) \
;         acc[ai][bj][m][n] = __builtin_amdgcn_mfma_f32_16x16x32_bf16(Bt[n][k], At[m][k], acc[ai][bj][m][n], 0, 0, 0); __builtin_amdgcn_s_setprio(0); } while (0)
; #define PG8_WAIT_V(n) asm volatile("s_waitcnt vmcnt(" #n ")" ::: "memory")
; #define PG8_WAIT_L(n) asm volatile("s_waitcnt lgkmcnt(" #n ")" ::: "memory")
; #define PG8_BAR __builtin_amdgcn_s_barrier()
; #define PG8_SCHED __builtin_amdgcn_sched_barrier(0)
; template <class Epi, class Sched, bool ALIGN_EPI = false, bool SP2 = false>
; __device__ __forceinline__ void gemm_phase(PG8_LAS unsigned char* lds, const Gemm g, const Sched& S, const Epi& E, int wave_s) {
;     ...
;             PG8_LDB(B0, 1, 0); PG8_LDB(B1, 1, 1); PG8_SCHED; PG8_LDA(At, 1, 0); PG8_STAGE(PG8_SA(0, 1), a2 + hstepA, voffA);
;             PG8_WAIT_V(8); PG8_WAIT_L(0); PG8_BAR; PG8_MMA(0, 0, At, B0); PG8_MMA(0, 1, At, B1); PG8_BAR; PG8_SCHED;
;             PG8_LDA(At, 1, 1); PG8_STAGE(PG8_SB(1, 0), b3, voffB); PG8_STAGE(PG8_SB(1, 1), b3 + hstepB, voffB); PG8_STAGE(PG8_SA(1, 0), a3, voffA);
;             PG8_WAIT_V(8); PG8_WAIT_L(0); PG8_BAR; PG8_MMA(1, 0, At, B0); PG8_MMA(1, 1, At, B1); PG8_BAR; PG8_SCHED;
	s_nop 0
	s_add_i32 s56, 0, 0x18000
	s_add_i32 s57, 0, 0x1c000
	ds_read_b128 v[146:149], v255 offset:32768
	ds_read_b128 v[150:153], v255 offset:33792
	ds_read_b128 v[154:157], v255 offset:34816
	ds_read_b128 v[158:161], v255 offset:35840
	ds_read_b128 v[162:165], v255 offset:49152
	ds_read_b128 v[182:185], v255 offset:50176
	ds_read_b128 v[186:189], v255 offset:51200
	ds_read_b128 v[190:193], v255 offset:52224
	s_add_u32 s38, s38, 0x80000
	s_addc_u32 s39, s39, 0
	s_mov_b32 m0, s45
	ds_read_b128 v[194:197], v145 offset:32768
	ds_read_b128 v[198:201], v145 offset:33792
	ds_read_b128 v[212:215], v145 offset:34816
	ds_read_b128 v[216:219], v145 offset:35840
	ds_read_b128 v[220:223], v145 offset:36864
	ds_read_b128 v[224:227], v145 offset:37888
	ds_read_b128 v[228:231], v145 offset:38912
	ds_read_b128 v[232:235], v145 offset:39936
	global_load_lds_dwordx4 v134, s[38:39]
	s_mov_b32 m0, s46
	s_nop 0
	global_load_lds_dwordx4 v132, s[38:39]
	s_waitcnt vmcnt(8)
	s_waitcnt lgkmcnt(0)
	s_barrier
	s_setprio 1
	s_waitcnt lgkmcnt(0)
	v_mfma_f32_16x16x32_bf16 v[128:131], v[146:149], v[194:197], v[128:131]
	v_mfma_f32_16x16x32_bf16 v[120:123], v[154:157], v[194:197], v[120:123]
	v_mfma_f32_16x16x32_bf16 v[112:115], v[146:149], v[212:215], v[112:115]
	v_mfma_f32_16x16x32_bf16 v[104:107], v[154:157], v[212:215], v[104:107]
	v_mfma_f32_16x16x32_bf16 v[96:99], v[146:149], v[220:223], v[96:99]
	v_mfma_f32_16x16x32_bf16 v[88:91], v[154:157], v[220:223], v[88:91]
	v_mfma_f32_16x16x32_bf16 v[80:83], v[146:149], v[228:231], v[80:83]
	v_mfma_f32_16x16x32_bf16 v[72:75], v[154:157], v[228:231], v[72:75]
	v_mfma_f32_16x16x32_bf16 v[128:131], v[150:153], v[198:201], v[128:131]
	v_mfma_f32_16x16x32_bf16 v[120:123], v[158:161], v[198:201], v[120:123]
	v_mfma_f32_16x16x32_bf16 v[112:115], v[150:153], v[216:219], v[112:115]
	v_mfma_f32_16x16x32_bf16 v[104:107], v[158:161], v[216:219], v[104:107]
	v_mfma_f32_16x16x32_bf16 v[96:99], v[150:153], v[224:227], v[96:99]
	v_mfma_f32_16x16x32_bf16 v[88:91], v[158:161], v[224:227], v[88:91]
	v_mfma_f32_16x16x32_bf16 v[80:83], v[150:153], v[232:235], v[80:83]
	v_mfma_f32_16x16x32_bf16 v[72:75], v[158:161], v[232:235], v[72:75]
	s_setprio 0
	s_setprio 1
	v_mfma_f32_16x16x32_bf16 v[124:127], v[162:165], v[194:197], v[124:127]
	v_mfma_f32_16x16x32_bf16 v[116:119], v[186:189], v[194:197], v[116:119]
	v_mfma_f32_16x16x32_bf16 v[108:111], v[162:165], v[212:215], v[108:111]
	v_mfma_f32_16x16x32_bf16 v[100:103], v[186:189], v[212:215], v[100:103]
	v_mfma_f32_16x16x32_bf16 v[92:95], v[162:165], v[220:223], v[92:95]
	v_mfma_f32_16x16x32_bf16 v[84:87], v[186:189], v[220:223], v[84:87]
	v_mfma_f32_16x16x32_bf16 v[76:79], v[162:165], v[228:231], v[76:79]
	v_mfma_f32_16x16x32_bf16 v[68:71], v[186:189], v[228:231], v[68:71]
	v_mfma_f32_16x16x32_bf16 v[124:127], v[182:185], v[198:201], v[124:127]
	v_mfma_f32_16x16x32_bf16 v[116:119], v[190:193], v[198:201], v[116:119]
	v_mfma_f32_16x16x32_bf16 v[108:111], v[182:185], v[216:219], v[108:111]
	v_mfma_f32_16x16x32_bf16 v[100:103], v[190:193], v[216:219], v[100:103]
	v_mfma_f32_16x16x32_bf16 v[92:95], v[182:185], v[224:227], v[92:95]
	v_mfma_f32_16x16x32_bf16 v[84:87], v[190:193], v[224:227], v[84:87]
	v_mfma_f32_16x16x32_bf16 v[76:79], v[182:185], v[232:235], v[76:79]
	v_mfma_f32_16x16x32_bf16 v[68:71], v[190:193], v[232:235], v[68:71]
	s_setprio 0
	s_barrier
	s_add_i32 s38, s56, s42
	s_mov_b32 m0, s38
	ds_read_b128 v[194:197], v145 offset:49152
	ds_read_b128 v[198:201], v145 offset:50176
	ds_read_b128 v[212:215], v145 offset:51200
	ds_read_b128 v[216:219], v145 offset:52224
	ds_read_b128 v[220:223], v145 offset:53248
	ds_read_b128 v[224:227], v145 offset:54272
	ds_read_b128 v[228:231], v145 offset:55296
	ds_read_b128 v[232:235], v145 offset:56320
	global_load_lds_dwordx4 v2, s[98:99]
	s_add_i32 m0, s38, 0x2000
	s_add_u32 s26, s26, 0x80080
	s_addc_u32 s27, s27, 0
	s_add_i32 s38, s57, s42
	global_load_lds_dwordx4 v0, s[98:99]
	s_mov_b32 m0, s38
	s_nop 0
	global_load_lds_dwordx4 v2, s[26:27]
	s_add_i32 m0, s38, 0x2000
	s_nop 0
	global_load_lds_dwordx4 v0, s[26:27]
	s_mov_b32 m0, s47
	s_nop 0
	global_load_lds_dwordx4 v134, s[100:101]
	s_mov_b32 m0, s48
	s_nop 0
	global_load_lds_dwordx4 v132, s[100:101]
	s_waitcnt vmcnt(8)
	s_waitcnt lgkmcnt(0)
	s_barrier
	s_setprio 1
	s_waitcnt lgkmcnt(0)
	v_mfma_f32_16x16x32_bf16 v[64:67], v[146:149], v[194:197], v[64:67]
	v_mfma_f32_16x16x32_bf16 v[56:59], v[154:157], v[194:197], v[56:59]
	v_mfma_f32_16x16x32_bf16 v[48:51], v[146:149], v[212:215], v[48:51]
	v_mfma_f32_16x16x32_bf16 v[40:43], v[154:157], v[212:215], v[40:43]
	v_mfma_f32_16x16x32_bf16 v[32:35], v[146:149], v[220:223], v[32:35]
	v_mfma_f32_16x16x32_bf16 v[24:27], v[154:157], v[220:223], v[24:27]
	v_mfma_f32_16x16x32_bf16 v[16:19], v[146:149], v[228:231], v[16:19]
	v_mfma_f32_16x16x32_bf16 v[8:11], v[154:157], v[228:231], v[8:11]
	v_mfma_f32_16x16x32_bf16 v[64:67], v[150:153], v[198:201], v[64:67]
	v_mfma_f32_16x16x32_bf16 v[56:59], v[158:161], v[198:201], v[56:59]
	v_mfma_f32_16x16x32_bf16 v[48:51], v[150:153], v[216:219], v[48:51]
	v_mfma_f32_16x16x32_bf16 v[40:43], v[158:161], v[216:219], v[40:43]
	v_mfma_f32_16x16x32_bf16 v[32:35], v[150:153], v[224:227], v[32:35]
	v_mfma_f32_16x16x32_bf16 v[24:27], v[158:161], v[224:227], v[24:27]
	v_mfma_f32_16x16x32_bf16 v[16:19], v[150:153], v[232:235], v[16:19]
	v_mfma_f32_16x16x32_bf16 v[8:11], v[158:161], v[232:235], v[8:11]
	s_setprio 0
	s_setprio 1
	v_mfma_f32_16x16x32_bf16 v[60:63], v[162:165], v[194:197], v[60:63]
	v_mfma_f32_16x16x32_bf16 v[52:55], v[186:189], v[194:197], v[52:55]
	v_mfma_f32_16x16x32_bf16 v[44:47], v[162:165], v[212:215], v[44:47]
	v_mfma_f32_16x16x32_bf16 v[36:39], v[186:189], v[212:215], v[36:39]
	v_mfma_f32_16x16x32_bf16 v[28:31], v[162:165], v[220:223], v[28:31]
	v_mfma_f32_16x16x32_bf16 v[20:23], v[186:189], v[220:223], v[20:23]
	v_mfma_f32_16x16x32_bf16 v[12:15], v[162:165], v[228:231], v[12:15]
	v_mfma_f32_16x16x32_bf16 v[4:7], v[186:189], v[228:231], v[4:7]
	v_mfma_f32_16x16x32_bf16 v[60:63], v[182:185], v[198:201], v[60:63]
	v_mfma_f32_16x16x32_bf16 v[52:55], v[190:193], v[198:201], v[52:55]
	v_mfma_f32_16x16x32_bf16 v[44:47], v[182:185], v[216:219], v[44:47]
	v_mfma_f32_16x16x32_bf16 v[36:39], v[190:193], v[216:219], v[36:39]
	v_mfma_f32_16x16x32_bf16 v[28:31], v[182:185], v[224:227], v[28:31]
	v_mfma_f32_16x16x32_bf16 v[20:23], v[190:193], v[224:227], v[20:23]
	v_mfma_f32_16x16x32_bf16 v[12:15], v[182:185], v[232:235], v[12:15]
	v_mfma_f32_16x16x32_bf16 v[4:7], v[190:193], v[232:235], v[4:7]
	s_setprio 0
	s_barrier
	s_add_i32 s55, s55, 2
	s_add_u32 s53, s53, 0x100
	s_addc_u32 s54, s54, 0
	s_add_u32 s18, s18, 0x100
	s_addc_u32 s19, s19, 0
	s_cmp_gt_u32 s55, 29
	s_cbranch_scc0 .LBB0_790
	s_and_b64 vcc, exec, s[6:7]
	s_cbranch_vccz .LBB0_793
	s_barrier

; #define PG8_STAGE(bufoff, gbase, voff) do { _Pragma("unroll") for (int _i = 0; _i < 2; ++_i) \
;         __builtin_amdgcn_global_load_lds((const unsigned*)((const char*)(gbase) + (voff)[_i]), (PG8_LAS unsigned*)(lds + (bufoff) + ldsw + _i * 8192), 16, 0, 0); } while (0)
; #define PG8_LDA(dst, b, h) do { _Pragma("unroll") for (int m = 0; m < 4; ++m) _Pragma("unroll") for (int k = 0; k < 2; ++k) dst[m][k] = *(const PG8_LAS bf16x8*)(lds + PG8_SA(b, h) + aoff + m * 2048 + k * 1024); } while (0)
; #define PG8_LDB(dst, b, h) do { _Pragma("unroll") for (int n = 0; n < 2; ++n) _Pragma("unroll") for (int k = 0; k < 2; ++k) dst[n][k] = *(const PG8_LAS bf16x8*)(lds + PG8_SB(b, h) + boff + n * 2048 + k * 1024); } while (0)
; #define PG8_MMA(ai, bj, At, Bt) do { __builtin_amdgcn_s_setprio(1); _Pragma("unroll") for (int m = 0; m < 4; ++m) _Pragma("unroll") for (int n = 0; n < 2; ++n) _Pragma("unroll") for (int k = 0; k < 2; ++k) \
;         acc[ai][bj][m][n] = __builtin_amdgcn_mfma_f32_16x16x32_bf16(Bt[n][k], At[m][k], acc[ai][bj][m][n], 0, 0, 0); __builtin_amdgcn_s_setprio(0); } while (0)
; #define PG8_WAIT_V(n) asm volatile("s_waitcnt vmcnt(" #n ")" ::: "memory")
; #define PG8_WAIT_L(n) asm volatile("s_waitcnt lgkmcnt(" #n ")" ::: "memory")
; #define PG8_BAR __builtin_amdgcn_s_barrier()
; #define PG8_SCHED __builtin_amdgcn_sched_barrier(0)
; template <class Epi, class Sched, bool ALIGN_EPI = false, bool SP2 = false>
; __device__ __forceinline__ void gemm_phase(PG8_LAS unsigned char* lds, const Gemm g, const Sched& S, const Epi& E, int wave_s) {
;     ...
;             const bool last = (t == nt - 2);
;             const char* a1 = cA + (size_t)(t + 1) * kstep;
;             const char* a2 = last ? nA : cA + (size_t)(t + 2) * kstep; const char* b2 = last ? nB : cB + (size_t)(t + 2) * kstep;
;             const char* a3 = a2 + kstep; const char* b3 = b2 + kstep;
;             if (last && has_next) S.a_ready(nxt);
;             if constexpr (SP2) {
;             PG8_LDB(B0, 0, 0); PG8_LDB(B1, 0, 1); PG8_SCHED; PG8_LDA(At, 0, 0); PG8_STAGE(PG8_SA(1, 1), a1 + hstepA, voffA);
;             PG8_WAIT_V(8); PG8_WAIT_L(0); PG8_BAR; PG8_MMA(0, 0, At, B0); PG8_MMA(0, 1, At, B1); PG8_BAR; PG8_SCHED;
;             PG8_LDA(At, 0, 1); PG8_STAGE(PG8_SB(0, 0), b2, voffB); PG8_STAGE(PG8_SB(0, 1), b2 + hstepB, voffB); PG8_STAGE(PG8_SA(0, 0), a2, voffA);
.LBB0_863:
	s_add_u32 s22, s20, 0x100
	s_addc_u32 s23, s21, 0
	s_add_i32 s54, 0, 0x10000
	s_cmpk_eq_i32 s53, 0x54
	s_cselect_b32 s27, s17, s23
	s_cselect_b32 s26, s16, s22
	s_cselect_b32 s25, s19, s37
	s_cselect_b32 s24, s18, s36
	s_add_i32 s55, 0, 0x14000
	ds_read_b128 v[132:135], v255
	ds_read_b128 v[136:139], v255 offset:1024
	ds_read_b128 v[140:143], v255 offset:2048
	ds_read_b128 v[144:147], v255 offset:3072
	ds_read_b128 v[148:151], v255 offset:16384
	ds_read_b128 v[160:163], v255 offset:17408
	ds_read_b128 v[164:167], v255 offset:18432
	ds_read_b128 v[188:191], v255 offset:19456
	v_lshl_add_u64 v[182:183], s[20:21], 0, v[158:159]
	s_add_i32 m0, s41, 0xc000
	ds_read_b128 v[192:195], v186
	ds_read_b128 v[196:199], v186 offset:1024
	ds_read_b128 v[212:215], v186 offset:2048
	ds_read_b128 v[216:219], v186 offset:3072
	ds_read_b128 v[220:223], v186 offset:4096
	ds_read_b128 v[224:227], v186 offset:5120
	ds_read_b128 v[228:231], v186 offset:6144
	ds_read_b128 v[232:235], v186 offset:7168
	global_load_lds_dwordx4 v[182:183], off
	v_lshl_add_u64 v[182:183], s[20:21], 0, v[156:157]
	s_add_i32 m0, s41, 0xe000
	s_nop 0
	global_load_lds_dwordx4 v[182:183], off
	s_waitcnt vmcnt(8)
	s_waitcnt lgkmcnt(0)
	s_barrier
	s_setprio 1
	s_waitcnt lgkmcnt(0)
	v_mfma_f32_16x16x32_bf16 v[128:131], v[132:135], v[192:195], v[128:131]
	v_mfma_f32_16x16x32_bf16 v[124:127], v[140:143], v[192:195], v[124:127]
	v_mfma_f32_16x16x32_bf16 v[120:123], v[132:135], v[212:215], v[120:123]
	v_mfma_f32_16x16x32_bf16 v[116:119], v[140:143], v[212:215], v[116:119]
	v_mfma_f32_16x16x32_bf16 v[96:99], v[132:135], v[220:223], v[96:99]
	v_mfma_f32_16x16x32_bf16 v[92:95], v[140:143], v[220:223], v[92:95]
	v_mfma_f32_16x16x32_bf16 v[80:83], v[132:135], v[228:231], v[80:83]
	v_mfma_f32_16x16x32_bf16 v[76:79], v[140:143], v[228:231], v[76:79]
	v_mfma_f32_16x16x32_bf16 v[128:131], v[136:139], v[196:199], v[128:131]
	v_mfma_f32_16x16x32_bf16 v[124:127], v[144:147], v[196:199], v[124:127]
	v_mfma_f32_16x16x32_bf16 v[120:123], v[136:139], v[216:219], v[120:123]
	v_mfma_f32_16x16x32_bf16 v[116:119], v[144:147], v[216:219], v[116:119]
	v_mfma_f32_16x16x32_bf16 v[96:99], v[136:139], v[224:227], v[96:99]
	v_mfma_f32_16x16x32_bf16 v[92:95], v[144:147], v[224:227], v[92:95]
	v_mfma_f32_16x16x32_bf16 v[80:83], v[136:139], v[232:235], v[80:83]
	v_mfma_f32_16x16x32_bf16 v[76:79], v[144:147], v[232:235], v[76:79]
	s_setprio 0
	s_setprio 1
	v_mfma_f32_16x16x32_bf16 v[112:115], v[148:151], v[192:195], v[112:115]
	v_mfma_f32_16x16x32_bf16 v[108:111], v[164:167], v[192:195], v[108:111]
	v_mfma_f32_16x16x32_bf16 v[104:107], v[148:151], v[212:215], v[104:107]
	v_mfma_f32_16x16x32_bf16 v[100:103], v[164:167], v[212:215], v[100:103]
	v_mfma_f32_16x16x32_bf16 v[88:91], v[148:151], v[220:223], v[88:91]
	v_mfma_f32_16x16x32_bf16 v[84:87], v[164:167], v[220:223], v[84:87]
	v_mfma_f32_16x16x32_bf16 v[72:75], v[148:151], v[228:231], v[72:75]
	v_mfma_f32_16x16x32_bf16 v[68:71], v[164:167], v[228:231], v[68:71]
	v_mfma_f32_16x16x32_bf16 v[112:115], v[160:163], v[196:199], v[112:115]
	v_mfma_f32_16x16x32_bf16 v[108:111], v[188:191], v[196:199], v[108:111]
	v_mfma_f32_16x16x32_bf16 v[104:107], v[160:163], v[216:219], v[104:107]
	v_mfma_f32_16x16x32_bf16 v[100:103], v[188:191], v[216:219], v[100:103]
	v_mfma_f32_16x16x32_bf16 v[88:91], v[160:163], v[224:227], v[88:91]
	v_mfma_f32_16x16x32_bf16 v[84:87], v[188:191], v[224:227], v[84:87]
	v_mfma_f32_16x16x32_bf16 v[72:75], v[160:163], v[232:235], v[72:75]
	v_mfma_f32_16x16x32_bf16 v[68:71], v[188:191], v[232:235], v[68:71]
	s_setprio 0
	s_barrier
	s_add_i32 s20, s54, s40
	s_add_u32 s98, s24, s60
	s_addc_u32 s99, s25, s61
	s_mov_b32 m0, s20
	ds_read_b128 v[192:195], v186 offset:16384
	ds_read_b128 v[196:199], v186 offset:17408
	ds_read_b128 v[212:215], v186 offset:18432
	ds_read_b128 v[216:219], v186 offset:19456
	ds_read_b128 v[220:223], v186 offset:20480
	ds_read_b128 v[224:227], v186 offset:21504
	ds_read_b128 v[228:231], v186 offset:22528
	ds_read_b128 v[232:235], v186 offset:23552
	global_load_lds_dwordx4 v2, s[24:25]
	s_add_i32 m0, s20, 0x2000
	s_add_u32 s20, s24, 0x160000
	s_addc_u32 s21, s25, 0
	s_add_i32 s54, s55, s40
	global_load_lds_dwordx4 v0, s[24:25]
	s_mov_b32 m0, s54
	s_add_u32 s100, s26, s60
	s_addc_u32 s101, s27, s61
	s_nop 0
	global_load_lds_dwordx4 v2, s[20:21]
	s_add_i32 m0, s54, 0x2000
	s_nop 0
	global_load_lds_dwordx4 v0, s[20:21]
	s_mov_b32 m0, s41
	s_nop 0
	global_load_lds_dwordx4 v154, s[26:27]
	s_mov_b32 m0, s42
	s_nop 0
	global_load_lds_dwordx4 v152, s[26:27]
	s_waitcnt vmcnt(8)
	s_waitcnt lgkmcnt(0)
	s_barrier
; #define PG8_STAGE(bufoff, gbase, voff) do { _Pragma("unroll") for (int _i = 0; _i < 2; ++_i) \
;         __builtin_amdgcn_global_load_lds((const unsigned*)((const char*)(gbase) + (voff)[_i]), (PG8_LAS unsigned*)(lds + (bufoff) + ldsw + _i * 8192), 16, 0, 0); } while (0)
; #define PG8_LDA(dst, b, h) do { _Pragma("unroll") for (int m = 0; m < 4; ++m) _Pragma("unroll") for (int k = 0; k < 2; ++k) dst[m][k] = *(const PG8_LAS bf16x8*)(lds + PG8_SA(b, h) + aoff + m * 2048 + k * 1024); } while (0)
; #define PG8_LDB(dst, b, h) do { _Pragma("unroll") for (int n = 0; n < 2; ++n) _Pragma("unroll") for (int k = 0; k < 2; ++k) dst[n][k] = *(const PG8_LAS bf16x8*)(lds + PG8_SB(b, h) + boff + n * 2048 + k * 1024); } while (0)
; #define PG8_MMA(ai, bj, At, Bt) do { __builtin_amdgcn_s_setprio(1); _Pragma("unroll") for (int m = 0; m < 4; ++m) _Pragma("unroll") for (int n = 0; n < 2; ++n) _Pragma("unroll") for (int k = 0; k < 2; ++k) \
;         acc[ai][bj][m][n] = __builtin_amdgcn_mfma_f32_16x16x32_bf16(Bt[n][k], At[m][k], acc[ai][bj][m][n], 0, 0, 0); __builtin_amdgcn_s_setprio(0); } while (0)
; #define PG8_WAIT_V(n) asm volatile("s_waitcnt vmcnt(" #n ")" ::: "memory")
; #define PG8_WAIT_L(n) asm volatile("s_waitcnt lgkmcnt(" #n ")" ::: "memory")
; #define PG8_BAR __builtin_amdgcn_s_barrier()
; #define PG8_SCHED __builtin_amdgcn_sched_barrier(0)
; template <class Epi, class Sched, bool ALIGN_EPI = false, bool SP2 = false>
; __device__ __forceinline__ void gemm_phase(PG8_LAS unsigned char* lds, const Gemm g, const Sched& S, const Epi& E, int wave_s) {
;     ...
;             PG8_WAIT_V(8); PG8_WAIT_L(0); PG8_BAR; PG8_MMA(1, 0, At, B0); PG8_MMA(1, 1, At, B1); PG8_BAR; PG8_SCHED;
;             PG8_LDB(B0, 1, 0); PG8_LDB(B1, 1, 1); PG8_SCHED; PG8_LDA(At, 1, 0); PG8_STAGE(PG8_SA(0, 1), a2 + hstepA, voffA);
;             PG8_WAIT_V(8); PG8_WAIT_L(0); PG8_BAR; PG8_MMA(0, 0, At, B0); PG8_MMA(0, 1, At, B1); PG8_BAR; PG8_SCHED;
	s_setprio 1
	s_waitcnt lgkmcnt(0)
	v_mfma_f32_16x16x32_bf16 v[64:67], v[132:135], v[192:195], v[64:67]
	v_mfma_f32_16x16x32_bf16 v[60:63], v[140:143], v[192:195], v[60:63]
	v_mfma_f32_16x16x32_bf16 v[48:51], v[132:135], v[212:215], v[48:51]
	v_mfma_f32_16x16x32_bf16 v[44:47], v[140:143], v[212:215], v[44:47]
	v_mfma_f32_16x16x32_bf16 v[32:35], v[132:135], v[220:223], v[32:35]
	v_mfma_f32_16x16x32_bf16 v[28:31], v[140:143], v[220:223], v[28:31]
	v_mfma_f32_16x16x32_bf16 v[16:19], v[132:135], v[228:231], v[16:19]
	v_mfma_f32_16x16x32_bf16 v[12:15], v[140:143], v[228:231], v[12:15]
	v_mfma_f32_16x16x32_bf16 v[64:67], v[136:139], v[196:199], v[64:67]
	v_mfma_f32_16x16x32_bf16 v[60:63], v[144:147], v[196:199], v[60:63]
	v_mfma_f32_16x16x32_bf16 v[48:51], v[136:139], v[216:219], v[48:51]
	v_mfma_f32_16x16x32_bf16 v[44:47], v[144:147], v[216:219], v[44:47]
	v_mfma_f32_16x16x32_bf16 v[32:35], v[136:139], v[224:227], v[32:35]
	v_mfma_f32_16x16x32_bf16 v[28:31], v[144:147], v[224:227], v[28:31]
	v_mfma_f32_16x16x32_bf16 v[16:19], v[136:139], v[232:235], v[16:19]
	v_mfma_f32_16x16x32_bf16 v[12:15], v[144:147], v[232:235], v[12:15]
	s_setprio 0
	s_setprio 1
	v_mfma_f32_16x16x32_bf16 v[56:59], v[148:151], v[192:195], v[56:59]
	v_mfma_f32_16x16x32_bf16 v[52:55], v[164:167], v[192:195], v[52:55]
	v_mfma_f32_16x16x32_bf16 v[40:43], v[148:151], v[212:215], v[40:43]
	v_mfma_f32_16x16x32_bf16 v[36:39], v[164:167], v[212:215], v[36:39]
	v_mfma_f32_16x16x32_bf16 v[24:27], v[148:151], v[220:223], v[24:27]
	v_mfma_f32_16x16x32_bf16 v[20:23], v[164:167], v[220:223], v[20:23]
	v_mfma_f32_16x16x32_bf16 v[8:11], v[148:151], v[228:231], v[8:11]
	v_mfma_f32_16x16x32_bf16 v[4:7], v[164:167], v[228:231], v[4:7]
	v_mfma_f32_16x16x32_bf16 v[56:59], v[160:163], v[196:199], v[56:59]
	v_mfma_f32_16x16x32_bf16 v[52:55], v[188:191], v[196:199], v[52:55]
	v_mfma_f32_16x16x32_bf16 v[40:43], v[160:163], v[216:219], v[40:43]
	v_mfma_f32_16x16x32_bf16 v[36:39], v[188:191], v[216:219], v[36:39]
	v_mfma_f32_16x16x32_bf16 v[24:27], v[160:163], v[224:227], v[24:27]
	v_mfma_f32_16x16x32_bf16 v[20:23], v[188:191], v[224:227], v[20:23]
	v_mfma_f32_16x16x32_bf16 v[8:11], v[160:163], v[232:235], v[8:11]
	v_mfma_f32_16x16x32_bf16 v[4:7], v[188:191], v[232:235], v[4:7]
	s_setprio 0
	s_barrier
	s_nop 0
	s_add_i32 s54, 0, 0x18000
	s_add_i32 s55, 0, 0x1c000
	ds_read_b128 v[132:135], v255 offset:32768
	ds_read_b128 v[136:139], v255 offset:33792
	ds_read_b128 v[140:143], v255 offset:34816
	ds_read_b128 v[144:147], v255 offset:35840
	ds_read_b128 v[148:151], v255 offset:49152
	ds_read_b128 v[160:163], v255 offset:50176
	ds_read_b128 v[164:167], v255 offset:51200
	ds_read_b128 v[188:191], v255 offset:52224
	s_add_u32 s20, s26, 0x160000
	s_addc_u32 s21, s27, 0
	s_mov_b32 m0, s43
	ds_read_b128 v[192:195], v186 offset:32768
	ds_read_b128 v[196:199], v186 offset:33792
	ds_read_b128 v[212:215], v186 offset:34816
	ds_read_b128 v[216:219], v186 offset:35840
	ds_read_b128 v[220:223], v186 offset:36864
	ds_read_b128 v[224:227], v186 offset:37888
	ds_read_b128 v[228:231], v186 offset:38912
	ds_read_b128 v[232:235], v186 offset:39936
	global_load_lds_dwordx4 v154, s[20:21]
	s_mov_b32 m0, s44
	s_nop 0
	global_load_lds_dwordx4 v152, s[20:21]
	s_waitcnt vmcnt(8)
	s_waitcnt lgkmcnt(0)
	s_barrier
	s_setprio 1
	s_waitcnt lgkmcnt(0)
	v_mfma_f32_16x16x32_bf16 v[128:131], v[132:135], v[192:195], v[128:131]
	v_mfma_f32_16x16x32_bf16 v[124:127], v[140:143], v[192:195], v[124:127]
	v_mfma_f32_16x16x32_bf16 v[120:123], v[132:135], v[212:215], v[120:123]
	v_mfma_f32_16x16x32_bf16 v[116:119], v[140:143], v[212:215], v[116:119]
	v_mfma_f32_16x16x32_bf16 v[96:99], v[132:135], v[220:223], v[96:99]
	v_mfma_f32_16x16x32_bf16 v[92:95], v[140:143], v[220:223], v[92:95]
	v_mfma_f32_16x16x32_bf16 v[80:83], v[132:135], v[228:231], v[80:83]
	v_mfma_f32_16x16x32_bf16 v[76:79], v[140:143], v[228:231], v[76:79]
	v_mfma_f32_16x16x32_bf16 v[128:131], v[136:139], v[196:199], v[128:131]
	v_mfma_f32_16x16x32_bf16 v[124:127], v[144:147], v[196:199], v[124:127]
	v_mfma_f32_16x16x32_bf16 v[120:123], v[136:139], v[216:219], v[120:123]
	v_mfma_f32_16x16x32_bf16 v[116:119], v[144:147], v[216:219], v[116:119]
	v_mfma_f32_16x16x32_bf16 v[96:99], v[136:139], v[224:227], v[96:99]
	v_mfma_f32_16x16x32_bf16 v[92:95], v[144:147], v[224:227], v[92:95]
	v_mfma_f32_16x16x32_bf16 v[80:83], v[136:139], v[232:235], v[80:83]
	v_mfma_f32_16x16x32_bf16 v[76:79], v[144:147], v[232:235], v[76:79]
	s_setprio 0
	s_setprio 1
	v_mfma_f32_16x16x32_bf16 v[112:115], v[148:151], v[192:195], v[112:115]
	v_mfma_f32_16x16x32_bf16 v[108:111], v[164:167], v[192:195], v[108:111]
	v_mfma_f32_16x16x32_bf16 v[104:107], v[148:151], v[212:215], v[104:107]
	v_mfma_f32_16x16x32_bf16 v[100:103], v[164:167], v[212:215], v[100:103]
	v_mfma_f32_16x16x32_bf16 v[88:91], v[148:151], v[220:223], v[88:91]
	v_mfma_f32_16x16x32_bf16 v[84:87], v[164:167], v[220:223], v[84:87]
	v_mfma_f32_16x16x32_bf16 v[72:75], v[148:151], v[228:231], v[72:75]
	v_mfma_f32_16x16x32_bf16 v[68:71], v[164:167], v[228:231], v[68:71]
	v_mfma_f32_16x16x32_bf16 v[112:115], v[160:163], v[196:199], v[112:115]
	v_mfma_f32_16x16x32_bf16 v[108:111], v[188:191], v[196:199], v[108:111]
	v_mfma_f32_16x16x32_bf16 v[104:107], v[160:163], v[216:219], v[104:107]
	v_mfma_f32_16x16x32_bf16 v[100:103], v[188:191], v[216:219], v[100:103]
	v_mfma_f32_16x16x32_bf16 v[88:91], v[160:163], v[224:227], v[88:91]
	v_mfma_f32_16x16x32_bf16 v[84:87], v[188:191], v[224:227], v[84:87]
	v_mfma_f32_16x16x32_bf16 v[72:75], v[160:163], v[232:235], v[72:75]
	v_mfma_f32_16x16x32_bf16 v[68:71], v[188:191], v[232:235], v[68:71]
	s_setprio 0
	s_barrier
; #define PG8_STAGE(bufoff, gbase, voff) do { _Pragma("unroll") for (int _i = 0; _i < 2; ++_i) \
;         __builtin_amdgcn_global_load_lds((const unsigned*)((const char*)(gbase) + (voff)[_i]), (PG8_LAS unsigned*)(lds + (bufoff) + ldsw + _i * 8192), 16, 0, 0); } while (0)
; #define PG8_LDA(dst, b, h) do { _Pragma("unroll") for (int m = 0; m < 4; ++m) _Pragma("unroll") for (int k = 0; k < 2; ++k) dst[m][k] = *(const PG8_LAS bf16x8*)(lds + PG8_SA(b, h) + aoff + m * 2048 + k * 1024); } while (0)
; #define PG8_WAIT_V(n) asm volatile("s_waitcnt vmcnt(" #n ")" ::: "memory")
; #define PG8_WAIT_L(n) asm volatile("s_waitcnt lgkmcnt(" #n ")" ::: "memory")
; #define PG8_BAR __builtin_amdgcn_s_barrier()
; template <class Epi, class Sched, bool ALIGN_EPI = false, bool SP2 = false>
; __device__ __forceinline__ void gemm_phase(PG8_LAS unsigned char* lds, const Gemm g, const Sched& S, const Epi& E, int wave_s) {
;     ...
;         for (int t = 0; t < nt; t += 2) {
;             const bool last = (t == nt - 2);
;             const char* a1 = cA + (size_t)(t + 1) * kstep;
;             const char* a2 = last ? nA : cA + (size_t)(t + 2) * kstep; const char* b2 = last ? nB : cB + (size_t)(t + 2) * kstep;
;             const char* a3 = a2 + kstep; const char* b3 = b2 + kstep;
;             if (last && has_next) S.a_ready(nxt);
;             if constexpr (SP2) {
;             PG8_LDB(B0, 0, 0); PG8_LDB(B1, 0, 1); PG8_SCHED; PG8_LDA(At, 0, 0); PG8_STAGE(PG8_SA(1, 1), a1 + hstepA, voffA);
;             PG8_WAIT_V(8); PG8_WAIT_L(0); PG8_BAR; PG8_MMA(0, 0, At, B0); PG8_MMA(0, 1, At, B1); PG8_BAR; PG8_SCHED;
;             PG8_LDA(At, 0, 1); PG8_STAGE(PG8_SB(0, 0), b2, voffB); PG8_STAGE(PG8_SB(0, 1), b2 + hstepB, voffB); PG8_STAGE(PG8_SA(0, 0), a2, voffA);
;             PG8_WAIT_V(8); PG8_WAIT_L(0); PG8_BAR; PG8_MMA(1, 0, At, B0); PG8_MMA(1, 1, At, B1); PG8_BAR; PG8_SCHED;
;             PG8_LDB(B0, 1, 0); PG8_LDB(B1, 1, 1); PG8_SCHED; PG8_LDA(At, 1, 0); PG8_STAGE(PG8_SA(0, 1), a2 + hstepA, voffA);
;             PG8_WAIT_V(8); PG8_WAIT_L(0); PG8_BAR; PG8_MMA(0, 0, At, B0); PG8_MMA(0, 1, At, B1); PG8_BAR; PG8_SCHED;
;             PG8_LDA(At, 1, 1); PG8_STAGE(PG8_SB(1, 0), b3, voffB); PG8_STAGE(PG8_SB(1, 1), b3 + hstepB, voffB); PG8_STAGE(PG8_SA(1, 0), a3, voffA);
;             PG8_WAIT_V(8); PG8_WAIT_L(0); PG8_BAR; PG8_MMA(1, 0, At, B0); PG8_MMA(1, 1, At, B1); PG8_BAR; PG8_SCHED;
	s_add_i32 s20, s54, s40
	s_mov_b32 m0, s20
	ds_read_b128 v[192:195], v186 offset:49152
	ds_read_b128 v[196:199], v186 offset:50176
	ds_read_b128 v[212:215], v186 offset:51200
	ds_read_b128 v[216:219], v186 offset:52224
	ds_read_b128 v[220:223], v186 offset:53248
	ds_read_b128 v[224:227], v186 offset:54272
	ds_read_b128 v[228:231], v186 offset:55296
	ds_read_b128 v[232:235], v186 offset:56320
	global_load_lds_dwordx4 v2, s[98:99]
	s_add_i32 m0, s20, 0x2000
	s_add_u32 s20, s24, 0x160080
	s_addc_u32 s21, s25, 0
	s_add_i32 s24, s55, s40
	global_load_lds_dwordx4 v0, s[98:99]
	s_mov_b32 m0, s24
	s_nop 0
	global_load_lds_dwordx4 v2, s[20:21]
	s_add_i32 m0, s24, 0x2000
	s_nop 0
	global_load_lds_dwordx4 v0, s[20:21]
	s_mov_b32 m0, s47
	s_nop 0
	global_load_lds_dwordx4 v154, s[100:101]
	s_mov_b32 m0, s48
	s_nop 0
	global_load_lds_dwordx4 v152, s[100:101]
	s_waitcnt vmcnt(8)
	s_waitcnt lgkmcnt(0)
	s_barrier
	s_setprio 1
	s_waitcnt lgkmcnt(0)
	v_mfma_f32_16x16x32_bf16 v[64:67], v[132:135], v[192:195], v[64:67]
	v_mfma_f32_16x16x32_bf16 v[60:63], v[140:143], v[192:195], v[60:63]
	v_mfma_f32_16x16x32_bf16 v[48:51], v[132:135], v[212:215], v[48:51]
	v_mfma_f32_16x16x32_bf16 v[44:47], v[140:143], v[212:215], v[44:47]
	v_mfma_f32_16x16x32_bf16 v[32:35], v[132:135], v[220:223], v[32:35]
	v_mfma_f32_16x16x32_bf16 v[28:31], v[140:143], v[220:223], v[28:31]
	v_mfma_f32_16x16x32_bf16 v[16:19], v[132:135], v[228:231], v[16:19]
	v_mfma_f32_16x16x32_bf16 v[12:15], v[140:143], v[228:231], v[12:15]
	v_mfma_f32_16x16x32_bf16 v[64:67], v[136:139], v[196:199], v[64:67]
	v_mfma_f32_16x16x32_bf16 v[60:63], v[144:147], v[196:199], v[60:63]
	v_mfma_f32_16x16x32_bf16 v[48:51], v[136:139], v[216:219], v[48:51]
	v_mfma_f32_16x16x32_bf16 v[44:47], v[144:147], v[216:219], v[44:47]
	v_mfma_f32_16x16x32_bf16 v[32:35], v[136:139], v[224:227], v[32:35]
	v_mfma_f32_16x16x32_bf16 v[28:31], v[144:147], v[224:227], v[28:31]
	v_mfma_f32_16x16x32_bf16 v[16:19], v[136:139], v[232:235], v[16:19]
	v_mfma_f32_16x16x32_bf16 v[12:15], v[144:147], v[232:235], v[12:15]
	s_setprio 0
	s_setprio 1
	v_mfma_f32_16x16x32_bf16 v[56:59], v[148:151], v[192:195], v[56:59]
	v_mfma_f32_16x16x32_bf16 v[52:55], v[164:167], v[192:195], v[52:55]
	v_mfma_f32_16x16x32_bf16 v[40:43], v[148:151], v[212:215], v[40:43]
	v_mfma_f32_16x16x32_bf16 v[36:39], v[164:167], v[212:215], v[36:39]
	v_mfma_f32_16x16x32_bf16 v[24:27], v[148:151], v[220:223], v[24:27]
	v_mfma_f32_16x16x32_bf16 v[20:23], v[164:167], v[220:223], v[20:23]
	v_mfma_f32_16x16x32_bf16 v[8:11], v[148:151], v[228:231], v[8:11]
	v_mfma_f32_16x16x32_bf16 v[4:7], v[164:167], v[228:231], v[4:7]
	v_mfma_f32_16x16x32_bf16 v[56:59], v[160:163], v[196:199], v[56:59]
	v_mfma_f32_16x16x32_bf16 v[52:55], v[188:191], v[196:199], v[52:55]
	v_mfma_f32_16x16x32_bf16 v[40:43], v[160:163], v[216:219], v[40:43]
	v_mfma_f32_16x16x32_bf16 v[36:39], v[188:191], v[216:219], v[36:39]
	v_mfma_f32_16x16x32_bf16 v[24:27], v[160:163], v[224:227], v[24:27]
	v_mfma_f32_16x16x32_bf16 v[20:23], v[188:191], v[224:227], v[20:23]
	v_mfma_f32_16x16x32_bf16 v[8:11], v[160:163], v[232:235], v[8:11]
	v_mfma_f32_16x16x32_bf16 v[4:7], v[188:191], v[232:235], v[4:7]
	s_setprio 0
	s_barrier
	s_add_i32 s53, s53, 2
	s_add_u32 s36, s36, 0x100
	s_addc_u32 s37, s37, 0
	s_cmpk_gt_u32 s53, 0x55
	s_mov_b64 s[20:21], s[22:23]
	s_cbranch_scc0 .LBB0_863
	s_and_b64 vcc, exec, s[6:7]
	s_cbranch_vccz .LBB0_866
	s_barrier
